# v10 + snapshot SALU adds placed in two of the M0 wait-state slots (two fewer s_nop per K-loop iteration)
# baseline (speedup 1.0000x reference)
.LBB0_295:
	ds_read_b128 v[146:149], v155
	ds_read_b128 v[160:163], v155 offset:1024
	ds_read_b128 v[164:167], v155 offset:2048
	ds_read_b128 v[168:171], v155 offset:3072
	ds_read_b128 v[172:175], v156
	ds_read_b128 v[176:179], v156 offset:1024
	ds_read_b128 v[180:183], v156 offset:2048
	ds_read_b128 v[184:187], v156 offset:3072
	s_add_u32 s23, s64, 0xfffc0080
	s_addc_u32 s33, s65, -1
	s_cmp_eq_u32 s92, 12
	s_cselect_b32 s73, s20, s33
	s_cselect_b32 s72, s21, s23
	s_cselect_b32 s71, s19, s91
	s_cselect_b32 s70, s55, s90
	s_add_i32 m0, s76, 0xc000
	ds_read_b128 v[188:191], v157
	ds_read_b128 v[192:195], v157 offset:1024
	ds_read_b128 v[196:199], v157 offset:2048
	ds_read_b128 v[200:203], v157 offset:3072
	ds_read_b128 v[204:207], v157 offset:4096
	ds_read_b128 v[208:211], v157 offset:5120
	ds_read_b128 v[212:215], v157 offset:6144
	ds_read_b128 v[216:219], v157 offset:7168
	global_load_lds_dwordx4 v138, s[64:65]
	s_add_i32 m0, s76, 0xe000
	s_nop 0
	global_load_lds_dwordx4 v140, s[64:65]
	s_waitcnt vmcnt(8)
	s_waitcnt lgkmcnt(0)
	s_barrier
	s_setprio 1
	v_mfma_f32_16x16x32_bf16 v[124:127], v[146:149], v[188:191], v[124:127]
	v_mfma_f32_16x16x32_bf16 v[120:123], v[164:167], v[188:191], v[120:123]
	v_mfma_f32_16x16x32_bf16 v[108:111], v[146:149], v[196:199], v[108:111]
	v_mfma_f32_16x16x32_bf16 v[104:107], v[164:167], v[196:199], v[104:107]
	v_mfma_f32_16x16x32_bf16 v[92:95], v[146:149], v[204:207], v[92:95]
	v_mfma_f32_16x16x32_bf16 v[88:91], v[164:167], v[204:207], v[88:91]
	v_mfma_f32_16x16x32_bf16 v[76:79], v[146:149], v[212:215], v[76:79]
	v_mfma_f32_16x16x32_bf16 v[72:75], v[164:167], v[212:215], v[72:75]
	v_mfma_f32_16x16x32_bf16 v[124:127], v[160:163], v[192:195], v[124:127]
	v_mfma_f32_16x16x32_bf16 v[120:123], v[168:171], v[192:195], v[120:123]
	v_mfma_f32_16x16x32_bf16 v[108:111], v[160:163], v[200:203], v[108:111]
	v_mfma_f32_16x16x32_bf16 v[104:107], v[168:171], v[200:203], v[104:107]
	v_mfma_f32_16x16x32_bf16 v[92:95], v[160:163], v[208:211], v[92:95]
	v_mfma_f32_16x16x32_bf16 v[88:91], v[168:171], v[208:211], v[88:91]
	v_mfma_f32_16x16x32_bf16 v[76:79], v[160:163], v[216:219], v[76:79]
	v_mfma_f32_16x16x32_bf16 v[72:75], v[168:171], v[216:219], v[72:75]
	v_mfma_f32_16x16x32_bf16 v[116:119], v[172:175], v[188:191], v[116:119]
	v_mfma_f32_16x16x32_bf16 v[112:115], v[180:183], v[188:191], v[112:115]
	v_mfma_f32_16x16x32_bf16 v[100:103], v[172:175], v[196:199], v[100:103]
	v_mfma_f32_16x16x32_bf16 v[96:99], v[180:183], v[196:199], v[96:99]
	v_mfma_f32_16x16x32_bf16 v[84:87], v[172:175], v[204:207], v[84:87]
	v_mfma_f32_16x16x32_bf16 v[80:83], v[180:183], v[204:207], v[80:83]
	v_mfma_f32_16x16x32_bf16 v[68:71], v[172:175], v[212:215], v[68:71]
	v_mfma_f32_16x16x32_bf16 v[64:67], v[180:183], v[212:215], v[64:67]
	v_mfma_f32_16x16x32_bf16 v[116:119], v[176:179], v[192:195], v[116:119]
	v_mfma_f32_16x16x32_bf16 v[112:115], v[184:187], v[192:195], v[112:115]
	v_mfma_f32_16x16x32_bf16 v[100:103], v[176:179], v[200:203], v[100:103]
	v_mfma_f32_16x16x32_bf16 v[96:99], v[184:187], v[200:203], v[96:99]
	v_mfma_f32_16x16x32_bf16 v[84:87], v[176:179], v[208:211], v[84:87]
	v_mfma_f32_16x16x32_bf16 v[80:83], v[184:187], v[208:211], v[80:83]
	v_mfma_f32_16x16x32_bf16 v[68:71], v[176:179], v[216:219], v[68:71]
	v_mfma_f32_16x16x32_bf16 v[64:67], v[184:187], v[216:219], v[64:67]
	s_setprio 0
	s_barrier
	s_add_i32 s23, s85, s74
	s_mov_b32 m0, s23
	ds_read_b128 v[188:191], v157 offset:16384
	ds_read_b128 v[192:195], v157 offset:17408
	ds_read_b128 v[196:199], v157 offset:18432
	ds_read_b128 v[200:203], v157 offset:19456
	ds_read_b128 v[204:207], v157 offset:20480
	ds_read_b128 v[208:211], v157 offset:21504
	ds_read_b128 v[212:215], v157 offset:22528
	ds_read_b128 v[216:219], v157 offset:23552
	global_load_lds_dwordx4 v132, s[70:71]
	s_add_i32 m0, s23, 0x2000
	s_add_u32 s94, s70, 0x40000
	s_addc_u32 s95, s71, 0
	s_add_i32 s23, s86, s74
	global_load_lds_dwordx4 v136, s[70:71]
	s_mov_b32 m0, s23
	s_add_u32 s98, s70, s10
	s_addc_u32 s99, s71, s11
	global_load_lds_dwordx4 v132, s[94:95]
	s_add_i32 m0, s23, 0x2000
	s_add_u32 s100, s72, s10
	s_addc_u32 s101, s73, s11
	global_load_lds_dwordx4 v136, s[94:95]
	s_mov_b32 m0, s76
	s_nop 0
	global_load_lds_dwordx4 v130, s[72:73]
	s_mov_b32 m0, s77
	s_nop 0
	global_load_lds_dwordx4 v134, s[72:73]
	s_waitcnt vmcnt(8)
	s_waitcnt lgkmcnt(0)
	s_barrier
	s_setprio 1
	v_mfma_f32_16x16x32_bf16 v[60:63], v[146:149], v[188:191], v[60:63]
	v_mfma_f32_16x16x32_bf16 v[56:59], v[164:167], v[188:191], v[56:59]
	v_mfma_f32_16x16x32_bf16 v[44:47], v[146:149], v[196:199], v[44:47]
	v_mfma_f32_16x16x32_bf16 v[40:43], v[164:167], v[196:199], v[40:43]
	v_mfma_f32_16x16x32_bf16 v[28:31], v[146:149], v[204:207], v[28:31]
	v_mfma_f32_16x16x32_bf16 v[24:27], v[164:167], v[204:207], v[24:27]
	v_mfma_f32_16x16x32_bf16 v[12:15], v[146:149], v[212:215], v[12:15]
	v_mfma_f32_16x16x32_bf16 v[8:11], v[164:167], v[212:215], v[8:11]
	v_mfma_f32_16x16x32_bf16 v[60:63], v[160:163], v[192:195], v[60:63]
	v_mfma_f32_16x16x32_bf16 v[56:59], v[168:171], v[192:195], v[56:59]
	v_mfma_f32_16x16x32_bf16 v[44:47], v[160:163], v[200:203], v[44:47]
	v_mfma_f32_16x16x32_bf16 v[40:43], v[168:171], v[200:203], v[40:43]
	v_mfma_f32_16x16x32_bf16 v[28:31], v[160:163], v[208:211], v[28:31]
	v_mfma_f32_16x16x32_bf16 v[24:27], v[168:171], v[208:211], v[24:27]
	v_mfma_f32_16x16x32_bf16 v[12:15], v[160:163], v[216:219], v[12:15]
	v_mfma_f32_16x16x32_bf16 v[8:11], v[168:171], v[216:219], v[8:11]
	v_mfma_f32_16x16x32_bf16 v[52:55], v[172:175], v[188:191], v[52:55]
	v_mfma_f32_16x16x32_bf16 v[48:51], v[180:183], v[188:191], v[48:51]
	v_mfma_f32_16x16x32_bf16 v[36:39], v[172:175], v[196:199], v[36:39]
	v_mfma_f32_16x16x32_bf16 v[32:35], v[180:183], v[196:199], v[32:35]
	v_mfma_f32_16x16x32_bf16 v[20:23], v[172:175], v[204:207], v[20:23]
	v_mfma_f32_16x16x32_bf16 v[16:19], v[180:183], v[204:207], v[16:19]
	v_mfma_f32_16x16x32_bf16 v[4:7], v[172:175], v[212:215], v[4:7]
	v_mfma_f32_16x16x32_bf16 v[0:3], v[180:183], v[212:215], v[0:3]
	v_mfma_f32_16x16x32_bf16 v[52:55], v[176:179], v[192:195], v[52:55]
	v_mfma_f32_16x16x32_bf16 v[48:51], v[184:187], v[192:195], v[48:51]
	v_mfma_f32_16x16x32_bf16 v[36:39], v[176:179], v[200:203], v[36:39]
	v_mfma_f32_16x16x32_bf16 v[32:35], v[184:187], v[200:203], v[32:35]
	v_mfma_f32_16x16x32_bf16 v[20:23], v[176:179], v[208:211], v[20:23]
	v_mfma_f32_16x16x32_bf16 v[16:19], v[184:187], v[208:211], v[16:19]
	v_mfma_f32_16x16x32_bf16 v[4:7], v[176:179], v[216:219], v[4:7]
	v_mfma_f32_16x16x32_bf16 v[0:3], v[184:187], v[216:219], v[0:3]
	s_setprio 0
	s_barrier
	s_add_i32 s23, 0, 0x18000
	v_add_u32_e32 v159, s23, v153
	s_add_i32 s33, 0, 0x1c000
	ds_read_b128 v[146:149], v159
	ds_read_b128 v[160:163], v159 offset:1024
	ds_read_b128 v[164:167], v159 offset:2048
	ds_read_b128 v[168:171], v159 offset:3072
	v_add_u32_e32 v159, s33, v153
	ds_read_b128 v[172:175], v159
	ds_read_b128 v[176:179], v159 offset:1024
	ds_read_b128 v[180:183], v159 offset:2048
	ds_read_b128 v[184:187], v159 offset:3072
	s_add_u32 s72, s72, 0x40000
	s_addc_u32 s73, s73, 0
	s_mov_b32 m0, s78
	ds_read_b128 v[188:191], v157 offset:32768
	ds_read_b128 v[192:195], v157 offset:33792
	ds_read_b128 v[196:199], v157 offset:34816
	ds_read_b128 v[200:203], v157 offset:35840
	ds_read_b128 v[204:207], v157 offset:36864
	ds_read_b128 v[208:211], v157 offset:37888
	ds_read_b128 v[212:215], v157 offset:38912
	ds_read_b128 v[216:219], v157 offset:39936
	global_load_lds_dwordx4 v130, s[72:73]
	s_mov_b32 m0, s79
	s_nop 0
	global_load_lds_dwordx4 v134, s[72:73]
	s_waitcnt vmcnt(8)
	s_waitcnt lgkmcnt(0)
	s_barrier
	s_setprio 1
	v_mfma_f32_16x16x32_bf16 v[124:127], v[146:149], v[188:191], v[124:127]
	v_mfma_f32_16x16x32_bf16 v[120:123], v[164:167], v[188:191], v[120:123]
	v_mfma_f32_16x16x32_bf16 v[108:111], v[146:149], v[196:199], v[108:111]
	v_mfma_f32_16x16x32_bf16 v[104:107], v[164:167], v[196:199], v[104:107]
	v_mfma_f32_16x16x32_bf16 v[92:95], v[146:149], v[204:207], v[92:95]
	v_mfma_f32_16x16x32_bf16 v[88:91], v[164:167], v[204:207], v[88:91]
	v_mfma_f32_16x16x32_bf16 v[76:79], v[146:149], v[212:215], v[76:79]
	v_mfma_f32_16x16x32_bf16 v[72:75], v[164:167], v[212:215], v[72:75]
	v_mfma_f32_16x16x32_bf16 v[124:127], v[160:163], v[192:195], v[124:127]
	v_mfma_f32_16x16x32_bf16 v[120:123], v[168:171], v[192:195], v[120:123]
	v_mfma_f32_16x16x32_bf16 v[108:111], v[160:163], v[200:203], v[108:111]
	v_mfma_f32_16x16x32_bf16 v[104:107], v[168:171], v[200:203], v[104:107]
	v_mfma_f32_16x16x32_bf16 v[92:95], v[160:163], v[208:211], v[92:95]
	v_mfma_f32_16x16x32_bf16 v[88:91], v[168:171], v[208:211], v[88:91]
	v_mfma_f32_16x16x32_bf16 v[76:79], v[160:163], v[216:219], v[76:79]
	v_mfma_f32_16x16x32_bf16 v[72:75], v[168:171], v[216:219], v[72:75]
	v_mfma_f32_16x16x32_bf16 v[116:119], v[172:175], v[188:191], v[116:119]
	v_mfma_f32_16x16x32_bf16 v[112:115], v[180:183], v[188:191], v[112:115]
	v_mfma_f32_16x16x32_bf16 v[100:103], v[172:175], v[196:199], v[100:103]
	v_mfma_f32_16x16x32_bf16 v[96:99], v[180:183], v[196:199], v[96:99]
	v_mfma_f32_16x16x32_bf16 v[84:87], v[172:175], v[204:207], v[84:87]
	v_mfma_f32_16x16x32_bf16 v[80:83], v[180:183], v[204:207], v[80:83]
	v_mfma_f32_16x16x32_bf16 v[68:71], v[172:175], v[212:215], v[68:71]
	v_mfma_f32_16x16x32_bf16 v[64:67], v[180:183], v[212:215], v[64:67]
	v_mfma_f32_16x16x32_bf16 v[116:119], v[176:179], v[192:195], v[116:119]
	v_mfma_f32_16x16x32_bf16 v[112:115], v[184:187], v[192:195], v[112:115]
	v_mfma_f32_16x16x32_bf16 v[100:103], v[176:179], v[200:203], v[100:103]
	v_mfma_f32_16x16x32_bf16 v[96:99], v[184:187], v[200:203], v[96:99]
	v_mfma_f32_16x16x32_bf16 v[84:87], v[176:179], v[208:211], v[84:87]
	v_mfma_f32_16x16x32_bf16 v[80:83], v[184:187], v[208:211], v[80:83]
	v_mfma_f32_16x16x32_bf16 v[68:71], v[176:179], v[216:219], v[68:71]
	v_mfma_f32_16x16x32_bf16 v[64:67], v[184:187], v[216:219], v[64:67]
	s_setprio 0
	s_barrier
	s_add_i32 s23, s23, s74
	s_mov_b32 m0, s23
	ds_read_b128 v[188:191], v157 offset:49152
	ds_read_b128 v[192:195], v157 offset:50176
	ds_read_b128 v[196:199], v157 offset:51200
	ds_read_b128 v[200:203], v157 offset:52224
	ds_read_b128 v[204:207], v157 offset:53248
	ds_read_b128 v[208:211], v157 offset:54272
	ds_read_b128 v[212:215], v157 offset:55296
	ds_read_b128 v[216:219], v157 offset:56320
	global_load_lds_dwordx4 v132, s[98:99]
	s_add_i32 m0, s23, 0x2000
	s_add_u32 s70, s70, 0x40080
	s_addc_u32 s71, s71, 0
	s_add_i32 s23, s33, s74
	global_load_lds_dwordx4 v136, s[98:99]
	s_mov_b32 m0, s23
	s_nop 0
	global_load_lds_dwordx4 v132, s[70:71]
	s_add_i32 m0, s23, 0x2000
	s_nop 0
	global_load_lds_dwordx4 v136, s[70:71]
	s_mov_b32 m0, s82
	s_nop 0
	global_load_lds_dwordx4 v130, s[100:101]
	s_mov_b32 m0, s83
	s_nop 0
	global_load_lds_dwordx4 v134, s[100:101]
	s_waitcnt vmcnt(8)
	s_waitcnt lgkmcnt(0)
	s_barrier
	s_setprio 1
	v_mfma_f32_16x16x32_bf16 v[60:63], v[146:149], v[188:191], v[60:63]
	v_mfma_f32_16x16x32_bf16 v[56:59], v[164:167], v[188:191], v[56:59]
	v_mfma_f32_16x16x32_bf16 v[44:47], v[146:149], v[196:199], v[44:47]
	v_mfma_f32_16x16x32_bf16 v[40:43], v[164:167], v[196:199], v[40:43]
	v_mfma_f32_16x16x32_bf16 v[28:31], v[146:149], v[204:207], v[28:31]
	v_mfma_f32_16x16x32_bf16 v[24:27], v[164:167], v[204:207], v[24:27]
	v_mfma_f32_16x16x32_bf16 v[12:15], v[146:149], v[212:215], v[12:15]
	v_mfma_f32_16x16x32_bf16 v[8:11], v[164:167], v[212:215], v[8:11]
	v_mfma_f32_16x16x32_bf16 v[60:63], v[160:163], v[192:195], v[60:63]
	v_mfma_f32_16x16x32_bf16 v[56:59], v[168:171], v[192:195], v[56:59]
	v_mfma_f32_16x16x32_bf16 v[44:47], v[160:163], v[200:203], v[44:47]
	v_mfma_f32_16x16x32_bf16 v[40:43], v[168:171], v[200:203], v[40:43]
	v_mfma_f32_16x16x32_bf16 v[28:31], v[160:163], v[208:211], v[28:31]
	v_mfma_f32_16x16x32_bf16 v[24:27], v[168:171], v[208:211], v[24:27]
	v_mfma_f32_16x16x32_bf16 v[12:15], v[160:163], v[216:219], v[12:15]
	v_mfma_f32_16x16x32_bf16 v[8:11], v[168:171], v[216:219], v[8:11]
	v_mfma_f32_16x16x32_bf16 v[52:55], v[172:175], v[188:191], v[52:55]
	v_mfma_f32_16x16x32_bf16 v[48:51], v[180:183], v[188:191], v[48:51]
	v_mfma_f32_16x16x32_bf16 v[36:39], v[172:175], v[196:199], v[36:39]
	v_mfma_f32_16x16x32_bf16 v[32:35], v[180:183], v[196:199], v[32:35]
	v_mfma_f32_16x16x32_bf16 v[20:23], v[172:175], v[204:207], v[20:23]
	v_mfma_f32_16x16x32_bf16 v[16:19], v[180:183], v[204:207], v[16:19]
	v_mfma_f32_16x16x32_bf16 v[4:7], v[172:175], v[212:215], v[4:7]
	v_mfma_f32_16x16x32_bf16 v[0:3], v[180:183], v[212:215], v[0:3]
	v_mfma_f32_16x16x32_bf16 v[52:55], v[176:179], v[192:195], v[52:55]
	v_mfma_f32_16x16x32_bf16 v[48:51], v[184:187], v[192:195], v[48:51]
	v_mfma_f32_16x16x32_bf16 v[36:39], v[176:179], v[200:203], v[36:39]
	v_mfma_f32_16x16x32_bf16 v[32:35], v[184:187], v[200:203], v[32:35]
	v_mfma_f32_16x16x32_bf16 v[20:23], v[176:179], v[208:211], v[20:23]
	v_mfma_f32_16x16x32_bf16 v[16:19], v[184:187], v[208:211], v[16:19]
	v_mfma_f32_16x16x32_bf16 v[4:7], v[176:179], v[216:219], v[4:7]
	v_mfma_f32_16x16x32_bf16 v[0:3], v[184:187], v[216:219], v[0:3]
	s_setprio 0
	s_barrier
	s_add_i32 s92, s92, 2
	s_add_u32 s64, s64, 0x100
	s_addc_u32 s65, s65, 0
	s_add_u32 s90, s90, 0x100
	s_addc_u32 s91, s91, 0
	s_cmp_gt_u32 s92, 13
	s_cbranch_scc0 .LBB0_295
	s_and_b64 vcc, exec, s[14:15]
	s_cbranch_vccz .LBB0_298
	s_barrier

.LBB0_437:
	ds_read_b128 v[146:149], v139
	ds_read_b128 v[150:153], v139 offset:1024
	ds_read_b128 v[154:157], v139 offset:2048
	ds_read_b128 v[158:161], v139 offset:3072
	ds_read_b128 v[162:165], v141
	ds_read_b128 v[166:169], v141 offset:1024
	ds_read_b128 v[170:173], v141 offset:2048
	ds_read_b128 v[174:177], v141 offset:3072
	s_add_u32 s10, s6, s8
	s_addc_u32 s11, s7, s9
	s_add_u32 s10, s10, 0x2300100
	s_addc_u32 s11, s11, 0
	s_add_u32 s23, s69, s8
	s_addc_u32 s33, s70, s9
	s_cmpk_eq_i32 s8, 0x700
	s_cselect_b32 s13, s3, s11
	s_cselect_b32 s12, s2, s10
	s_cselect_b32 s11, s1, s33
	s_cselect_b32 s10, s0, s23
	s_mov_b32 m0, s72
	v_lshl_add_u64 v[210:211], v[134:135], 0, s[8:9]
	ds_read_b128 v[178:181], v142
	ds_read_b128 v[182:185], v142 offset:1024
	ds_read_b128 v[186:189], v142 offset:2048
	ds_read_b128 v[190:193], v142 offset:3072
	ds_read_b128 v[194:197], v142 offset:4096
	ds_read_b128 v[198:201], v142 offset:5120
	ds_read_b128 v[202:205], v142 offset:6144
	ds_read_b128 v[206:209], v142 offset:7168
	global_load_lds_dwordx4 v[210:211], off
	v_lshl_add_u64 v[210:211], v[136:137], 0, s[8:9]
	s_mov_b32 m0, s73
	s_nop 0
	global_load_lds_dwordx4 v[210:211], off
	s_waitcnt vmcnt(8)
	s_waitcnt lgkmcnt(0)
	s_barrier
	s_setprio 1
	v_mfma_f32_16x16x32_bf16 v[124:127], v[146:149], v[178:181], v[124:127]
	v_mfma_f32_16x16x32_bf16 v[120:123], v[154:157], v[178:181], v[120:123]
	v_mfma_f32_16x16x32_bf16 v[108:111], v[146:149], v[186:189], v[108:111]
	v_mfma_f32_16x16x32_bf16 v[104:107], v[154:157], v[186:189], v[104:107]
	v_mfma_f32_16x16x32_bf16 v[92:95], v[146:149], v[194:197], v[92:95]
	v_mfma_f32_16x16x32_bf16 v[88:91], v[154:157], v[194:197], v[88:91]
	v_mfma_f32_16x16x32_bf16 v[76:79], v[146:149], v[202:205], v[76:79]
	v_mfma_f32_16x16x32_bf16 v[72:75], v[154:157], v[202:205], v[72:75]
	v_mfma_f32_16x16x32_bf16 v[124:127], v[150:153], v[182:185], v[124:127]
	v_mfma_f32_16x16x32_bf16 v[120:123], v[158:161], v[182:185], v[120:123]
	v_mfma_f32_16x16x32_bf16 v[108:111], v[150:153], v[190:193], v[108:111]
	v_mfma_f32_16x16x32_bf16 v[104:107], v[158:161], v[190:193], v[104:107]
	v_mfma_f32_16x16x32_bf16 v[92:95], v[150:153], v[198:201], v[92:95]
	v_mfma_f32_16x16x32_bf16 v[88:91], v[158:161], v[198:201], v[88:91]
	v_mfma_f32_16x16x32_bf16 v[76:79], v[150:153], v[206:209], v[76:79]
	v_mfma_f32_16x16x32_bf16 v[72:75], v[158:161], v[206:209], v[72:75]
	v_mfma_f32_16x16x32_bf16 v[116:119], v[162:165], v[178:181], v[116:119]
	v_mfma_f32_16x16x32_bf16 v[112:115], v[170:173], v[178:181], v[112:115]
	v_mfma_f32_16x16x32_bf16 v[100:103], v[162:165], v[186:189], v[100:103]
	v_mfma_f32_16x16x32_bf16 v[96:99], v[170:173], v[186:189], v[96:99]
	v_mfma_f32_16x16x32_bf16 v[84:87], v[162:165], v[194:197], v[84:87]
	v_mfma_f32_16x16x32_bf16 v[80:83], v[170:173], v[194:197], v[80:83]
	v_mfma_f32_16x16x32_bf16 v[68:71], v[162:165], v[202:205], v[68:71]
	v_mfma_f32_16x16x32_bf16 v[64:67], v[170:173], v[202:205], v[64:67]
	v_mfma_f32_16x16x32_bf16 v[116:119], v[166:169], v[182:185], v[116:119]
	v_mfma_f32_16x16x32_bf16 v[112:115], v[174:177], v[182:185], v[112:115]
	v_mfma_f32_16x16x32_bf16 v[100:103], v[166:169], v[190:193], v[100:103]
	v_mfma_f32_16x16x32_bf16 v[96:99], v[174:177], v[190:193], v[96:99]
	v_mfma_f32_16x16x32_bf16 v[84:87], v[166:169], v[198:201], v[84:87]
	v_mfma_f32_16x16x32_bf16 v[80:83], v[174:177], v[198:201], v[80:83]
	v_mfma_f32_16x16x32_bf16 v[68:71], v[166:169], v[206:209], v[68:71]
	v_mfma_f32_16x16x32_bf16 v[64:67], v[174:177], v[206:209], v[64:67]
	s_setprio 0
	s_barrier
	s_mov_b32 m0, s74
	s_add_u32 s82, s10, 0x40000
	ds_read_b128 v[178:181], v142 offset:16384
	ds_read_b128 v[182:185], v142 offset:17408
	ds_read_b128 v[186:189], v142 offset:18432
	ds_read_b128 v[190:193], v142 offset:19456
	ds_read_b128 v[194:197], v142 offset:20480
	ds_read_b128 v[198:201], v142 offset:21504
	ds_read_b128 v[202:205], v142 offset:22528
	ds_read_b128 v[206:209], v142 offset:23552
	global_load_lds_dwordx4 v132, s[10:11]
	s_mov_b32 m0, s75
	s_addc_u32 s83, s11, 0
	global_load_lds_dwordx4 v130, s[10:11]
	s_mov_b32 m0, s76
	s_add_u32 s98, s10, s4
	s_addc_u32 s99, s11, s5
	global_load_lds_dwordx4 v132, s[82:83]
	s_mov_b32 m0, s77
	s_add_u32 s100, s12, s4
	s_addc_u32 s101, s13, s5
	global_load_lds_dwordx4 v130, s[82:83]
	s_mov_b32 m0, s17
	s_nop 0
	global_load_lds_dwordx4 v132, s[12:13]
	s_mov_b32 m0, s20
	s_nop 0
	global_load_lds_dwordx4 v130, s[12:13]
	s_waitcnt vmcnt(8)
	s_waitcnt lgkmcnt(0)
	s_barrier
	s_setprio 1
	v_mfma_f32_16x16x32_bf16 v[60:63], v[146:149], v[178:181], v[60:63]
	v_mfma_f32_16x16x32_bf16 v[56:59], v[154:157], v[178:181], v[56:59]
	v_mfma_f32_16x16x32_bf16 v[44:47], v[146:149], v[186:189], v[44:47]
	v_mfma_f32_16x16x32_bf16 v[40:43], v[154:157], v[186:189], v[40:43]
	v_mfma_f32_16x16x32_bf16 v[28:31], v[146:149], v[194:197], v[28:31]
	v_mfma_f32_16x16x32_bf16 v[24:27], v[154:157], v[194:197], v[24:27]
	v_mfma_f32_16x16x32_bf16 v[12:15], v[146:149], v[202:205], v[12:15]
	v_mfma_f32_16x16x32_bf16 v[8:11], v[154:157], v[202:205], v[8:11]
	v_mfma_f32_16x16x32_bf16 v[60:63], v[150:153], v[182:185], v[60:63]
	v_mfma_f32_16x16x32_bf16 v[56:59], v[158:161], v[182:185], v[56:59]
	v_mfma_f32_16x16x32_bf16 v[44:47], v[150:153], v[190:193], v[44:47]
	v_mfma_f32_16x16x32_bf16 v[40:43], v[158:161], v[190:193], v[40:43]
	v_mfma_f32_16x16x32_bf16 v[28:31], v[150:153], v[198:201], v[28:31]
	v_mfma_f32_16x16x32_bf16 v[24:27], v[158:161], v[198:201], v[24:27]
	v_mfma_f32_16x16x32_bf16 v[12:15], v[150:153], v[206:209], v[12:15]
	v_mfma_f32_16x16x32_bf16 v[8:11], v[158:161], v[206:209], v[8:11]
	v_mfma_f32_16x16x32_bf16 v[52:55], v[162:165], v[178:181], v[52:55]
	v_mfma_f32_16x16x32_bf16 v[48:51], v[170:173], v[178:181], v[48:51]
	v_mfma_f32_16x16x32_bf16 v[36:39], v[162:165], v[186:189], v[36:39]
	v_mfma_f32_16x16x32_bf16 v[32:35], v[170:173], v[186:189], v[32:35]
	v_mfma_f32_16x16x32_bf16 v[20:23], v[162:165], v[194:197], v[20:23]
	v_mfma_f32_16x16x32_bf16 v[16:19], v[170:173], v[194:197], v[16:19]
	v_mfma_f32_16x16x32_bf16 v[4:7], v[162:165], v[202:205], v[4:7]
	v_mfma_f32_16x16x32_bf16 v[0:3], v[170:173], v[202:205], v[0:3]
	v_mfma_f32_16x16x32_bf16 v[52:55], v[166:169], v[182:185], v[52:55]
	v_mfma_f32_16x16x32_bf16 v[48:51], v[174:177], v[182:185], v[48:51]
	v_mfma_f32_16x16x32_bf16 v[36:39], v[166:169], v[190:193], v[36:39]
	v_mfma_f32_16x16x32_bf16 v[32:35], v[174:177], v[190:193], v[32:35]
	v_mfma_f32_16x16x32_bf16 v[20:23], v[166:169], v[198:201], v[20:23]
	v_mfma_f32_16x16x32_bf16 v[16:19], v[174:177], v[198:201], v[16:19]
	v_mfma_f32_16x16x32_bf16 v[4:7], v[166:169], v[206:209], v[4:7]
	v_mfma_f32_16x16x32_bf16 v[0:3], v[174:177], v[206:209], v[0:3]
	s_setprio 0
	s_barrier
	ds_read_b128 v[146:149], v143
	ds_read_b128 v[150:153], v143 offset:1024
	ds_read_b128 v[154:157], v143 offset:2048
	ds_read_b128 v[158:161], v143 offset:3072
	ds_read_b128 v[162:165], v144
	ds_read_b128 v[166:169], v144 offset:1024
	ds_read_b128 v[170:173], v144 offset:2048
	ds_read_b128 v[174:177], v144 offset:3072
	s_add_u32 s12, s12, 0x40000
	s_addc_u32 s13, s13, 0
	s_mov_b32 m0, s21
	ds_read_b128 v[178:181], v142 offset:32768
	ds_read_b128 v[182:185], v142 offset:33792
	ds_read_b128 v[186:189], v142 offset:34816
	ds_read_b128 v[190:193], v142 offset:35840
	ds_read_b128 v[194:197], v142 offset:36864
	ds_read_b128 v[198:201], v142 offset:37888
	ds_read_b128 v[202:205], v142 offset:38912
	ds_read_b128 v[206:209], v142 offset:39936
	global_load_lds_dwordx4 v132, s[12:13]
	s_mov_b32 m0, s58
	s_nop 0
	global_load_lds_dwordx4 v130, s[12:13]
	s_waitcnt vmcnt(8)
	s_waitcnt lgkmcnt(0)
	s_barrier
	s_setprio 1
	v_mfma_f32_16x16x32_bf16 v[124:127], v[146:149], v[178:181], v[124:127]
	v_mfma_f32_16x16x32_bf16 v[120:123], v[154:157], v[178:181], v[120:123]
	v_mfma_f32_16x16x32_bf16 v[108:111], v[146:149], v[186:189], v[108:111]
	v_mfma_f32_16x16x32_bf16 v[104:107], v[154:157], v[186:189], v[104:107]
	v_mfma_f32_16x16x32_bf16 v[92:95], v[146:149], v[194:197], v[92:95]
	v_mfma_f32_16x16x32_bf16 v[88:91], v[154:157], v[194:197], v[88:91]
	v_mfma_f32_16x16x32_bf16 v[76:79], v[146:149], v[202:205], v[76:79]
	v_mfma_f32_16x16x32_bf16 v[72:75], v[154:157], v[202:205], v[72:75]
	v_mfma_f32_16x16x32_bf16 v[124:127], v[150:153], v[182:185], v[124:127]
	v_mfma_f32_16x16x32_bf16 v[120:123], v[158:161], v[182:185], v[120:123]
	v_mfma_f32_16x16x32_bf16 v[108:111], v[150:153], v[190:193], v[108:111]
	v_mfma_f32_16x16x32_bf16 v[104:107], v[158:161], v[190:193], v[104:107]
	v_mfma_f32_16x16x32_bf16 v[92:95], v[150:153], v[198:201], v[92:95]
	v_mfma_f32_16x16x32_bf16 v[88:91], v[158:161], v[198:201], v[88:91]
	v_mfma_f32_16x16x32_bf16 v[76:79], v[150:153], v[206:209], v[76:79]
	v_mfma_f32_16x16x32_bf16 v[72:75], v[158:161], v[206:209], v[72:75]
	v_mfma_f32_16x16x32_bf16 v[116:119], v[162:165], v[178:181], v[116:119]
	v_mfma_f32_16x16x32_bf16 v[112:115], v[170:173], v[178:181], v[112:115]
	v_mfma_f32_16x16x32_bf16 v[100:103], v[162:165], v[186:189], v[100:103]
	v_mfma_f32_16x16x32_bf16 v[96:99], v[170:173], v[186:189], v[96:99]
	v_mfma_f32_16x16x32_bf16 v[84:87], v[162:165], v[194:197], v[84:87]
	v_mfma_f32_16x16x32_bf16 v[80:83], v[170:173], v[194:197], v[80:83]
	v_mfma_f32_16x16x32_bf16 v[68:71], v[162:165], v[202:205], v[68:71]
	v_mfma_f32_16x16x32_bf16 v[64:67], v[170:173], v[202:205], v[64:67]
	v_mfma_f32_16x16x32_bf16 v[116:119], v[166:169], v[182:185], v[116:119]
	v_mfma_f32_16x16x32_bf16 v[112:115], v[174:177], v[182:185], v[112:115]
	v_mfma_f32_16x16x32_bf16 v[100:103], v[166:169], v[190:193], v[100:103]
	v_mfma_f32_16x16x32_bf16 v[96:99], v[174:177], v[190:193], v[96:99]
	v_mfma_f32_16x16x32_bf16 v[84:87], v[166:169], v[198:201], v[84:87]
	v_mfma_f32_16x16x32_bf16 v[80:83], v[174:177], v[198:201], v[80:83]
	v_mfma_f32_16x16x32_bf16 v[68:71], v[166:169], v[206:209], v[68:71]
	v_mfma_f32_16x16x32_bf16 v[64:67], v[174:177], v[206:209], v[64:67]
	s_setprio 0
	s_barrier
	s_mov_b32 m0, s78
	s_add_u32 s10, s10, 0x40080
	ds_read_b128 v[178:181], v142 offset:49152
	ds_read_b128 v[182:185], v142 offset:50176
	ds_read_b128 v[186:189], v142 offset:51200
	ds_read_b128 v[190:193], v142 offset:52224
	ds_read_b128 v[194:197], v142 offset:53248
	ds_read_b128 v[198:201], v142 offset:54272
	ds_read_b128 v[202:205], v142 offset:55296
	ds_read_b128 v[206:209], v142 offset:56320
	global_load_lds_dwordx4 v132, s[98:99]
	s_mov_b32 m0, s79
	s_addc_u32 s11, s11, 0
	global_load_lds_dwordx4 v130, s[98:99]
	s_mov_b32 m0, s80
	s_nop 0
	global_load_lds_dwordx4 v132, s[10:11]
	s_mov_b32 m0, s81
	s_nop 0
	global_load_lds_dwordx4 v130, s[10:11]
	s_mov_b32 m0, s65
	s_nop 0
	global_load_lds_dwordx4 v132, s[100:101]
	s_mov_b32 m0, s68
	s_nop 0
	global_load_lds_dwordx4 v130, s[100:101]
	s_waitcnt vmcnt(8)
	s_waitcnt lgkmcnt(0)
	s_barrier
	s_setprio 1
	v_mfma_f32_16x16x32_bf16 v[60:63], v[146:149], v[178:181], v[60:63]
	v_mfma_f32_16x16x32_bf16 v[56:59], v[154:157], v[178:181], v[56:59]
	v_mfma_f32_16x16x32_bf16 v[44:47], v[146:149], v[186:189], v[44:47]
	v_mfma_f32_16x16x32_bf16 v[40:43], v[154:157], v[186:189], v[40:43]
	v_mfma_f32_16x16x32_bf16 v[28:31], v[146:149], v[194:197], v[28:31]
	v_mfma_f32_16x16x32_bf16 v[24:27], v[154:157], v[194:197], v[24:27]
	v_mfma_f32_16x16x32_bf16 v[12:15], v[146:149], v[202:205], v[12:15]
	v_mfma_f32_16x16x32_bf16 v[8:11], v[154:157], v[202:205], v[8:11]
	v_mfma_f32_16x16x32_bf16 v[60:63], v[150:153], v[182:185], v[60:63]
	v_mfma_f32_16x16x32_bf16 v[56:59], v[158:161], v[182:185], v[56:59]
	v_mfma_f32_16x16x32_bf16 v[44:47], v[150:153], v[190:193], v[44:47]
	v_mfma_f32_16x16x32_bf16 v[40:43], v[158:161], v[190:193], v[40:43]
	v_mfma_f32_16x16x32_bf16 v[28:31], v[150:153], v[198:201], v[28:31]
	v_mfma_f32_16x16x32_bf16 v[24:27], v[158:161], v[198:201], v[24:27]
	v_mfma_f32_16x16x32_bf16 v[12:15], v[150:153], v[206:209], v[12:15]
	v_mfma_f32_16x16x32_bf16 v[8:11], v[158:161], v[206:209], v[8:11]
	v_mfma_f32_16x16x32_bf16 v[52:55], v[162:165], v[178:181], v[52:55]
	v_mfma_f32_16x16x32_bf16 v[48:51], v[170:173], v[178:181], v[48:51]
	v_mfma_f32_16x16x32_bf16 v[36:39], v[162:165], v[186:189], v[36:39]
	v_mfma_f32_16x16x32_bf16 v[32:35], v[170:173], v[186:189], v[32:35]
	v_mfma_f32_16x16x32_bf16 v[20:23], v[162:165], v[194:197], v[20:23]
	v_mfma_f32_16x16x32_bf16 v[16:19], v[170:173], v[194:197], v[16:19]
	v_mfma_f32_16x16x32_bf16 v[4:7], v[162:165], v[202:205], v[4:7]
	v_mfma_f32_16x16x32_bf16 v[0:3], v[170:173], v[202:205], v[0:3]
	v_mfma_f32_16x16x32_bf16 v[52:55], v[166:169], v[182:185], v[52:55]
	v_mfma_f32_16x16x32_bf16 v[48:51], v[174:177], v[182:185], v[48:51]
	v_mfma_f32_16x16x32_bf16 v[36:39], v[166:169], v[190:193], v[36:39]
	v_mfma_f32_16x16x32_bf16 v[32:35], v[174:177], v[190:193], v[32:35]
	v_mfma_f32_16x16x32_bf16 v[20:23], v[166:169], v[198:201], v[20:23]
	v_mfma_f32_16x16x32_bf16 v[16:19], v[174:177], v[198:201], v[16:19]
	v_mfma_f32_16x16x32_bf16 v[4:7], v[166:169], v[206:209], v[4:7]
	v_mfma_f32_16x16x32_bf16 v[0:3], v[174:177], v[206:209], v[0:3]
	s_setprio 0
	s_barrier
	s_add_i32 s71, s71, 2
	s_add_u32 s8, s8, 0x100
	s_addc_u32 s9, s9, 0
	s_cmp_gt_u32 s71, 13
	s_cbranch_scc0 .LBB0_437
	s_add_u32 s4, s28, 0x2f41000
	s_addc_u32 s5, s29, 0
	s_lshl_b32 s0, s16, 8
	s_add_i32 s64, s64, s0
	v_or_b32_e32 v130, s64, v140
	v_mov_b32_e32 v131, 0
	v_lshl_add_u64 v[132:133], v[130:131], 2, s[4:5]
	global_load_dword v149, v[132:133], off
	v_lshl_or_b32 v134, v138, 2, s59
	v_mov_b32_e32 v148, 0x358637bd
	s_lshl_b32 s13, s15, 8
	s_mov_b32 s6, 0x800000
	s_movk_i32 s0, 0x36c
	v_or_b32_e32 v146, s13, v134
	s_and_b32 s9, s13, 0x300
	v_mov_b32_e32 v150, s13
	s_lshl_b32 s13, s64, 2
	v_mov_b32_e32 v142, 0x80
	s_movk_i32 s10, 0xec
	v_lshlrev_b32_e32 v138, 1, v134
	v_bitop3_b32 v134, v134, s0, v150 bitop3:0xc8
	s_and_b32 s0, s13, 0xfffffc00
	v_bitop3_b32 v154, v146, s10, v142 bitop3:0xc8
	s_or_b32 s10, s0, s9
	s_mov_b32 s1, 0x4880000
	s_cmp_gt_u32 s15, 3
	v_mov_b32_e32 v136, 0xcf
	s_mov_b32 s2, 0x2b00000
	s_cselect_b32 s0, s1, 0x4080000
	s_movk_i32 s3, 0x37c
	s_movk_i32 s8, 0x3ec
	v_bitop3_b32 v152, s64, v136, v140 bitop3:0xc8
	s_cselect_b32 s1, s2, 0x2700000
	s_add_u32 s2, s26, s0
	v_bitop3_b32 v136, v146, s3, 16 bitop3:0xc8
	v_bitop3_b32 v153, v146, s8, v142 bitop3:0xc8
	v_or_b32_e32 v152, s10, v152
	s_addc_u32 s3, s27, 0
	s_movk_i32 s7, 0x7c
	s_movk_i32 s11, 0x3fc
	v_mov_b32_e32 v144, 0x90
	s_movk_i32 s12, 0xfc
	v_lshlrev_b64 v[150:151], 12, v[130:131]
	v_lshlrev_b32_e32 v142, 2, v153
	v_ashrrev_i32_e32 v153, 31, v152
	s_add_u32 s0, s28, s1
	v_mov_b32_e32 v147, v131
	v_bitop3_b32 v140, v146, s7, 16 bitop3:0xc8
	v_bitop3_b32 v155, v146, s11, v144 bitop3:0xc8
	v_bitop3_b32 v167, v146, s12, v144 bitop3:0xc8
	v_lshlrev_b32_e32 v146, 2, v134
	v_lshlrev_b64 v[152:153], 9, v[152:153]
	v_lshl_add_u64 v[150:151], s[2:3], 0, v[150:151]
	s_addc_u32 s1, s29, 0
	v_mov_b32_e32 v139, v131
	v_lshlrev_b32_e32 v144, 2, v136
	v_lshlrev_b32_e32 v134, 1, v140
	v_lshlrev_b32_e32 v136, 1, v154
	v_lshlrev_b32_e32 v140, 2, v155
	v_lshl_add_u64 v[154:155], v[150:151], 0, v[146:147]
	v_lshl_add_u64 v[152:153], s[0:1], 0, v[152:153]
	v_mov_b32_e32 v145, v131
	v_mov_b32_e32 v135, v131
	v_mov_b32_e32 v143, v131
	v_mov_b32_e32 v137, v131
	v_lshl_add_u64 v[156:157], v[150:151], 0, v[144:145]
	v_lshl_add_u64 v[162:163], v[152:153], 0, v[134:135]
	v_mov_b32_e32 v141, v131
	v_lshl_add_u64 v[158:159], v[150:151], 0, v[142:143]
	v_lshl_add_u64 v[164:165], v[152:153], 0, v[136:137]
	v_lshl_add_u64 v[150:151], v[150:151], 0, v[140:141]
	s_movk_i32 s7, 0xdf
	s_movk_i32 s8, 0xef
	s_cmpk_lt_u32 s14, 0x100
	s_waitcnt vmcnt(0)
	v_fmamk_f32 v149, v149, 0x3a800000, v148
	v_mul_f32_e32 v160, 0x4b800000, v149
	v_cmp_gt_f32_e32 vcc, s6, v149
	s_nop 1
	v_cndmask_b32_e32 v149, v149, v160, vcc
	v_rsq_f32_e32 v149, v149
	v_lshl_add_u64 v[160:161], v[152:153], 0, v[138:139]
	v_mul_f32_e32 v166, 0x45800000, v149
	v_cndmask_b32_e32 v166, v149, v166, vcc
	v_pk_mul_f32 v[126:127], v[126:127], v[166:167] op_sel_hi:[1,0]
	v_pk_mul_f32 v[124:125], v[124:125], v[166:167] op_sel_hi:[1,0]
	v_pk_mul_f32 v[120:121], v[120:121], v[166:167] op_sel_hi:[1,0]
	global_store_dwordx4 v[154:155], v[124:127], off
	v_pk_mul_f32 v[122:123], v[122:123], v[166:167] op_sel_hi:[1,0]
	v_pk_mul_f32 v[116:117], v[116:117], v[166:167] op_sel_hi:[1,0]
	v_cvt_pk_bf16_f32 v124, v124, v125
	v_cvt_pk_bf16_f32 v125, v126, v127
	global_store_dwordx2 v[160:161], v[124:125], off
	global_store_dwordx4 v[156:157], v[120:123], off
	v_pk_mul_f32 v[118:119], v[118:119], v[166:167] op_sel_hi:[1,0]
	v_pk_mul_f32 v[112:113], v[112:113], v[166:167] op_sel_hi:[1,0]
	v_cvt_pk_bf16_f32 v120, v120, v121
	v_cvt_pk_bf16_f32 v121, v122, v123
	global_store_dwordx2 v[162:163], v[120:121], off
	global_store_dwordx4 v[158:159], v[116:119], off
	v_pk_mul_f32 v[114:115], v[114:115], v[166:167] op_sel_hi:[1,0]
	v_bitop3_b32 v120, v130, s7, 16 bitop3:0xc8
	v_cvt_pk_bf16_f32 v116, v116, v117
	v_cvt_pk_bf16_f32 v117, v118, v119
	global_store_dwordx2 v[164:165], v[116:117], off
	global_store_dwordx4 v[150:151], v[112:115], off
	v_cvt_pk_bf16_f32 v116, v112, v113
	v_cvt_pk_bf16_f32 v117, v114, v115
	v_or_b32_e32 v120, s10, v120
	v_ashrrev_i32_e32 v121, 31, v120
	v_lshlrev_b32_e32 v112, 1, v167
	v_mov_b32_e32 v113, v131
	v_lshl_add_u64 v[114:115], v[152:153], 0, v[112:113]
	global_store_dwordx2 v[114:115], v[116:117], off
	v_or_b32_e32 v114, 16, v130
	v_mov_b32_e32 v115, v131
	v_lshl_add_u64 v[116:117], v[114:115], 2, s[4:5]
	global_load_dword v149, v[116:117], off
	v_lshlrev_b64 v[114:115], 12, v[114:115]
	v_lshlrev_b64 v[120:121], 9, v[120:121]
	v_lshl_add_u64 v[114:115], s[2:3], 0, v[114:115]
	v_lshl_add_u64 v[122:123], v[114:115], 0, v[146:147]
	v_lshl_add_u64 v[120:121], s[0:1], 0, v[120:121]
	v_lshl_add_u64 v[150:151], v[120:121], 0, v[138:139]
	v_lshl_add_u64 v[124:125], v[114:115], 0, v[144:145]
	v_mov_b32_e32 v117, v131
	v_or_b32_e32 v116, 32, v130
	v_lshl_add_u64 v[126:127], v[114:115], 0, v[142:143]
	v_lshl_add_u64 v[154:155], v[120:121], 0, v[136:137]
	v_lshl_add_u64 v[118:119], v[116:117], 2, s[4:5]
	v_lshl_add_u64 v[114:115], v[114:115], 0, v[140:141]
	s_waitcnt vmcnt(0)
	v_fmamk_f32 v149, v149, 0x3a800000, v148
	v_mul_f32_e32 v152, 0x4b800000, v149
	v_cmp_gt_f32_e32 vcc, s6, v149
	s_nop 1
	v_cndmask_b32_e32 v149, v149, v152, vcc
	v_rsq_f32_e32 v149, v149
	v_lshl_add_u64 v[152:153], v[120:121], 0, v[134:135]
	v_lshl_add_u64 v[120:121], v[120:121], 0, v[112:113]
	v_mul_f32_e32 v156, 0x45800000, v149
	v_cndmask_b32_e32 v156, v149, v156, vcc
	v_pk_mul_f32 v[110:111], v[110:111], v[156:157] op_sel_hi:[1,0]
	v_pk_mul_f32 v[108:109], v[108:109], v[156:157] op_sel_hi:[1,0]
	v_pk_mul_f32 v[104:105], v[104:105], v[156:157] op_sel_hi:[1,0]
	global_store_dwordx4 v[122:123], v[108:111], off
	v_pk_mul_f32 v[106:107], v[106:107], v[156:157] op_sel_hi:[1,0]
	v_pk_mul_f32 v[100:101], v[100:101], v[156:157] op_sel_hi:[1,0]
	v_cvt_pk_bf16_f32 v108, v108, v109
	v_cvt_pk_bf16_f32 v109, v110, v111
	global_store_dwordx2 v[150:151], v[108:109], off
	global_store_dwordx4 v[124:125], v[104:107], off
	v_pk_mul_f32 v[102:103], v[102:103], v[156:157] op_sel_hi:[1,0]
	v_pk_mul_f32 v[96:97], v[96:97], v[156:157] op_sel_hi:[1,0]
	v_cvt_pk_bf16_f32 v104, v104, v105
	v_cvt_pk_bf16_f32 v105, v106, v107
	global_store_dwordx2 v[152:153], v[104:105], off
	global_store_dwordx4 v[126:127], v[100:103], off
	v_pk_mul_f32 v[98:99], v[98:99], v[156:157] op_sel_hi:[1,0]
	s_nop 0
	v_cvt_pk_bf16_f32 v100, v100, v101
	v_cvt_pk_bf16_f32 v101, v102, v103
	global_store_dwordx2 v[154:155], v[100:101], off
	global_store_dwordx4 v[114:115], v[96:99], off
	v_bitop3_b32 v102, v130, s8, 32 bitop3:0xc8
	v_or_b32_e32 v102, s10, v102
	v_cvt_pk_bf16_f32 v96, v96, v97
	v_cvt_pk_bf16_f32 v97, v98, v99
	global_store_dwordx2 v[120:121], v[96:97], off
	global_load_dword v114, v[118:119], off
	v_lshlrev_b64 v[98:99], 12, v[116:117]
	v_ashrrev_i32_e32 v103, 31, v102
	v_lshlrev_b64 v[102:103], 9, v[102:103]
	v_lshl_add_u64 v[98:99], s[2:3], 0, v[98:99]
	v_lshl_add_u64 v[104:105], v[98:99], 0, v[146:147]
	v_lshl_add_u64 v[102:103], s[0:1], 0, v[102:103]
	v_lshl_add_u64 v[110:111], v[102:103], 0, v[138:139]
	v_lshl_add_u64 v[106:107], v[98:99], 0, v[144:145]
	v_mov_b32_e32 v97, v131
	v_or_b32_e32 v96, 48, v130
	v_lshl_add_u64 v[108:109], v[98:99], 0, v[142:143]
	v_lshl_add_u64 v[116:117], v[102:103], 0, v[136:137]
	v_lshl_add_u64 v[100:101], v[96:97], 2, s[4:5]
	v_lshl_add_u64 v[98:99], v[98:99], 0, v[140:141]
	s_movk_i32 s4, 0xff
	s_movk_i32 s5, 0xcf
	s_waitcnt vmcnt(0)
	v_fmamk_f32 v114, v114, 0x3a800000, v148
	v_mul_f32_e32 v115, 0x4b800000, v114
	v_cmp_gt_f32_e32 vcc, s6, v114
	s_nop 1
	v_cndmask_b32_e32 v114, v114, v115, vcc
	v_rsq_f32_e32 v118, v114
	v_lshl_add_u64 v[114:115], v[102:103], 0, v[134:135]
	v_lshl_add_u64 v[102:103], v[102:103], 0, v[112:113]
	v_mul_f32_e32 v119, 0x45800000, v118
	v_cndmask_b32_e32 v118, v118, v119, vcc
	v_pk_mul_f32 v[94:95], v[94:95], v[118:119] op_sel_hi:[1,0]
	v_pk_mul_f32 v[92:93], v[92:93], v[118:119] op_sel_hi:[1,0]
	v_pk_mul_f32 v[88:89], v[88:89], v[118:119] op_sel_hi:[1,0]
	global_store_dwordx4 v[104:105], v[92:95], off
	v_pk_mul_f32 v[90:91], v[90:91], v[118:119] op_sel_hi:[1,0]
	v_pk_mul_f32 v[84:85], v[84:85], v[118:119] op_sel_hi:[1,0]
	v_cvt_pk_bf16_f32 v92, v92, v93
	v_cvt_pk_bf16_f32 v93, v94, v95
	global_store_dwordx2 v[110:111], v[92:93], off
	global_store_dwordx4 v[106:107], v[88:91], off
	v_pk_mul_f32 v[86:87], v[86:87], v[118:119] op_sel_hi:[1,0]
	v_pk_mul_f32 v[80:81], v[80:81], v[118:119] op_sel_hi:[1,0]
	v_cvt_pk_bf16_f32 v88, v88, v89
	v_cvt_pk_bf16_f32 v89, v90, v91
	global_store_dwordx2 v[114:115], v[88:89], off
	global_store_dwordx4 v[108:109], v[84:87], off
	v_pk_mul_f32 v[82:83], v[82:83], v[118:119] op_sel_hi:[1,0]
	s_nop 0
	v_cvt_pk_bf16_f32 v84, v84, v85
	v_cvt_pk_bf16_f32 v85, v86, v87
	global_store_dwordx2 v[116:117], v[84:85], off
	global_store_dwordx4 v[98:99], v[80:83], off
	s_nop 1
	v_cvt_pk_bf16_f32 v80, v80, v81
	v_cvt_pk_bf16_f32 v81, v82, v83
	global_store_dwordx2 v[102:103], v[80:81], off
	global_load_dword v92, v[100:101], off
	v_lshlrev_b64 v[80:81], 12, v[96:97]
	v_bitop3_b32 v82, v130, s4, 48 bitop3:0xc8
	v_or_b32_e32 v82, s10, v82
	v_ashrrev_i32_e32 v83, 31, v82
	v_lshlrev_b64 v[82:83], 9, v[82:83]
	v_lshl_add_u64 v[80:81], s[2:3], 0, v[80:81]
	v_lshl_add_u64 v[84:85], v[80:81], 0, v[146:147]
	v_lshl_add_u64 v[82:83], s[0:1], 0, v[82:83]
	v_lshl_add_u64 v[90:91], v[82:83], 0, v[138:139]
	v_lshl_add_u64 v[86:87], v[80:81], 0, v[144:145]
	v_lshl_add_u64 v[88:89], v[80:81], 0, v[142:143]
	v_lshl_add_u64 v[94:95], v[82:83], 0, v[136:137]
	v_lshl_add_u64 v[80:81], v[80:81], 0, v[140:141]
	s_waitcnt vmcnt(0)
	v_fmamk_f32 v92, v92, 0x3a800000, v148
	v_mul_f32_e32 v93, 0x4b800000, v92
	v_cmp_gt_f32_e32 vcc, s6, v92
	s_nop 1
	v_cndmask_b32_e32 v92, v92, v93, vcc
	v_rsq_f32_e32 v96, v92
	v_lshl_add_u64 v[92:93], v[82:83], 0, v[134:135]
	v_lshl_add_u64 v[82:83], v[82:83], 0, v[112:113]
	v_mul_f32_e32 v97, 0x45800000, v96
	v_cndmask_b32_e32 v96, v96, v97, vcc
	v_pk_mul_f32 v[78:79], v[78:79], v[96:97] op_sel_hi:[1,0]
	v_pk_mul_f32 v[76:77], v[76:77], v[96:97] op_sel_hi:[1,0]
	v_pk_mul_f32 v[72:73], v[72:73], v[96:97] op_sel_hi:[1,0]
	global_store_dwordx4 v[84:85], v[76:79], off
	v_pk_mul_f32 v[74:75], v[74:75], v[96:97] op_sel_hi:[1,0]
	v_pk_mul_f32 v[68:69], v[68:69], v[96:97] op_sel_hi:[1,0]
	v_cvt_pk_bf16_f32 v76, v76, v77
	v_cvt_pk_bf16_f32 v77, v78, v79
	global_store_dwordx2 v[90:91], v[76:77], off
	global_store_dwordx4 v[86:87], v[72:75], off
	v_pk_mul_f32 v[70:71], v[70:71], v[96:97] op_sel_hi:[1,0]
	v_pk_mul_f32 v[64:65], v[64:65], v[96:97] op_sel_hi:[1,0]
	v_cvt_pk_bf16_f32 v72, v72, v73
	v_cvt_pk_bf16_f32 v73, v74, v75
	global_store_dwordx2 v[92:93], v[72:73], off
	global_store_dwordx4 v[88:89], v[68:71], off
	v_pk_mul_f32 v[66:67], v[66:67], v[96:97] op_sel_hi:[1,0]
	s_nop 0
	v_cvt_pk_bf16_f32 v68, v68, v69
	v_cvt_pk_bf16_f32 v69, v70, v71
	global_store_dwordx2 v[94:95], v[68:69], off
	global_store_dwordx4 v[80:81], v[64:67], off
	s_nop 1
	v_cvt_pk_bf16_f32 v64, v64, v65
	v_cvt_pk_bf16_f32 v65, v66, v67
	global_store_dwordx2 v[82:83], v[64:65], off
	global_load_dword v76, v[132:133], off offset:512
	v_add_u32_e32 v64, 0x80, v130
	v_mov_b32_e32 v65, v131
	v_lshlrev_b32_e32 v68, 2, v64
	v_lshlrev_b64 v[66:67], 12, v[64:65]
	v_and_b32_e32 v65, 0xfffffc00, v68
	v_or_b32_e32 v81, s9, v65
	v_and_or_b32 v64, v64, s5, v81
	v_ashrrev_i32_e32 v65, 31, v64
	v_lshlrev_b64 v[64:65], 9, v[64:65]
	v_lshl_add_u64 v[66:67], s[2:3], 0, v[66:67]
	v_lshl_add_u64 v[68:69], v[66:67], 0, v[146:147]
	v_lshl_add_u64 v[64:65], s[0:1], 0, v[64:65]
	v_lshl_add_u64 v[74:75], v[64:65], 0, v[138:139]
	v_lshl_add_u64 v[70:71], v[66:67], 0, v[144:145]
	v_lshl_add_u64 v[72:73], v[66:67], 0, v[142:143]
	v_lshl_add_u64 v[78:79], v[64:65], 0, v[136:137]
	v_lshl_add_u64 v[66:67], v[66:67], 0, v[140:141]
	s_waitcnt vmcnt(0)
	v_fmamk_f32 v76, v76, 0x3a800000, v148
	v_mul_f32_e32 v77, 0x4b800000, v76
	v_cmp_gt_f32_e32 vcc, s6, v76
	s_nop 1
	v_cndmask_b32_e32 v76, v76, v77, vcc
	v_rsq_f32_e32 v80, v76
	v_lshl_add_u64 v[76:77], v[64:65], 0, v[134:135]
	v_lshl_add_u64 v[64:65], v[64:65], 0, v[112:113]
	v_mul_f32_e32 v82, 0x45800000, v80
	v_cndmask_b32_e32 v80, v80, v82, vcc
	v_pk_mul_f32 v[62:63], v[62:63], v[80:81] op_sel_hi:[1,0]
	v_pk_mul_f32 v[60:61], v[60:61], v[80:81] op_sel_hi:[1,0]
	v_pk_mul_f32 v[56:57], v[56:57], v[80:81] op_sel_hi:[1,0]
	global_store_dwordx4 v[68:69], v[60:63], off
	v_pk_mul_f32 v[58:59], v[58:59], v[80:81] op_sel_hi:[1,0]
	v_pk_mul_f32 v[52:53], v[52:53], v[80:81] op_sel_hi:[1,0]
	v_cvt_pk_bf16_f32 v60, v60, v61
	v_cvt_pk_bf16_f32 v61, v62, v63
	global_store_dwordx2 v[74:75], v[60:61], off
	global_store_dwordx4 v[70:71], v[56:59], off
	v_pk_mul_f32 v[54:55], v[54:55], v[80:81] op_sel_hi:[1,0]
	v_pk_mul_f32 v[48:49], v[48:49], v[80:81] op_sel_hi:[1,0]
	v_cvt_pk_bf16_f32 v56, v56, v57
	v_cvt_pk_bf16_f32 v57, v58, v59
	global_store_dwordx2 v[76:77], v[56:57], off
	global_store_dwordx4 v[72:73], v[52:55], off
	v_pk_mul_f32 v[50:51], v[50:51], v[80:81] op_sel_hi:[1,0]
	s_nop 0
	v_cvt_pk_bf16_f32 v52, v52, v53
	v_cvt_pk_bf16_f32 v53, v54, v55
	global_store_dwordx2 v[78:79], v[52:53], off
	global_store_dwordx4 v[66:67], v[48:51], off
	s_nop 1
	v_cvt_pk_bf16_f32 v48, v48, v49
	v_cvt_pk_bf16_f32 v49, v50, v51
	global_store_dwordx2 v[64:65], v[48:49], off
	global_load_dword v60, v[132:133], off offset:576
	v_mov_b32_e32 v49, v131
	v_add_u32_e32 v48, 0x90, v130
	v_lshlrev_b64 v[50:51], 12, v[48:49]
	v_and_or_b32 v48, v48, s7, v81
	v_ashrrev_i32_e32 v49, 31, v48
	v_lshlrev_b64 v[48:49], 9, v[48:49]
	v_lshl_add_u64 v[50:51], s[2:3], 0, v[50:51]
	v_lshl_add_u64 v[52:53], v[50:51], 0, v[146:147]
	v_lshl_add_u64 v[48:49], s[0:1], 0, v[48:49]
	v_lshl_add_u64 v[58:59], v[48:49], 0, v[138:139]
	v_lshl_add_u64 v[54:55], v[50:51], 0, v[144:145]
	v_lshl_add_u64 v[56:57], v[50:51], 0, v[142:143]
	v_lshl_add_u64 v[62:63], v[48:49], 0, v[136:137]
	v_lshl_add_u64 v[50:51], v[50:51], 0, v[140:141]
	s_waitcnt vmcnt(0)
	v_fmamk_f32 v60, v60, 0x3a800000, v148
	v_mul_f32_e32 v61, 0x4b800000, v60
	v_cmp_gt_f32_e32 vcc, s6, v60
	s_nop 1
	v_cndmask_b32_e32 v60, v60, v61, vcc
	v_rsq_f32_e32 v64, v60
	v_lshl_add_u64 v[60:61], v[48:49], 0, v[134:135]
	v_lshl_add_u64 v[48:49], v[48:49], 0, v[112:113]
	v_mul_f32_e32 v65, 0x45800000, v64
	v_cndmask_b32_e32 v64, v64, v65, vcc
	v_pk_mul_f32 v[46:47], v[46:47], v[64:65] op_sel_hi:[1,0]
	v_pk_mul_f32 v[44:45], v[44:45], v[64:65] op_sel_hi:[1,0]
	v_pk_mul_f32 v[40:41], v[40:41], v[64:65] op_sel_hi:[1,0]
	global_store_dwordx4 v[52:53], v[44:47], off
	v_pk_mul_f32 v[42:43], v[42:43], v[64:65] op_sel_hi:[1,0]
	v_pk_mul_f32 v[36:37], v[36:37], v[64:65] op_sel_hi:[1,0]
	v_cvt_pk_bf16_f32 v44, v44, v45
	v_cvt_pk_bf16_f32 v45, v46, v47
	global_store_dwordx2 v[58:59], v[44:45], off
	global_store_dwordx4 v[54:55], v[40:43], off
	v_pk_mul_f32 v[38:39], v[38:39], v[64:65] op_sel_hi:[1,0]
	v_pk_mul_f32 v[32:33], v[32:33], v[64:65] op_sel_hi:[1,0]
	v_cvt_pk_bf16_f32 v40, v40, v41
	v_cvt_pk_bf16_f32 v41, v42, v43
	global_store_dwordx2 v[60:61], v[40:41], off
	global_store_dwordx4 v[56:57], v[36:39], off
	v_pk_mul_f32 v[34:35], v[34:35], v[64:65] op_sel_hi:[1,0]
	s_nop 0
	v_cvt_pk_bf16_f32 v36, v36, v37
	v_cvt_pk_bf16_f32 v37, v38, v39
	global_store_dwordx2 v[62:63], v[36:37], off
	global_store_dwordx4 v[50:51], v[32:35], off
	s_nop 1
	v_cvt_pk_bf16_f32 v32, v32, v33
	v_cvt_pk_bf16_f32 v33, v34, v35
	global_store_dwordx2 v[48:49], v[32:33], off
	global_load_dword v44, v[132:133], off offset:640
	v_mov_b32_e32 v33, v131
	v_add_u32_e32 v32, 0xa0, v130
	v_lshlrev_b64 v[34:35], 12, v[32:33]
	v_and_or_b32 v32, v32, s8, v81
	v_ashrrev_i32_e32 v33, 31, v32
	v_lshlrev_b64 v[32:33], 9, v[32:33]
	v_lshl_add_u64 v[34:35], s[2:3], 0, v[34:35]
	v_lshl_add_u64 v[36:37], v[34:35], 0, v[146:147]
	v_lshl_add_u64 v[32:33], s[0:1], 0, v[32:33]
	v_lshl_add_u64 v[42:43], v[32:33], 0, v[138:139]
	v_lshl_add_u64 v[38:39], v[34:35], 0, v[144:145]
	v_lshl_add_u64 v[40:41], v[34:35], 0, v[142:143]
	v_lshl_add_u64 v[46:47], v[32:33], 0, v[136:137]
	v_lshl_add_u64 v[34:35], v[34:35], 0, v[140:141]
	v_add_u32_e32 v130, 0xb0, v130
	s_waitcnt vmcnt(0)
	v_fmamk_f32 v44, v44, 0x3a800000, v148
	v_mul_f32_e32 v45, 0x4b800000, v44
	v_cmp_gt_f32_e32 vcc, s6, v44
	s_nop 1
	v_cndmask_b32_e32 v44, v44, v45, vcc
	v_rsq_f32_e32 v48, v44
	v_lshl_add_u64 v[44:45], v[32:33], 0, v[134:135]
	v_lshl_add_u64 v[32:33], v[32:33], 0, v[112:113]
	v_mul_f32_e32 v49, 0x45800000, v48
	v_cndmask_b32_e32 v48, v48, v49, vcc
	v_pk_mul_f32 v[30:31], v[30:31], v[48:49] op_sel_hi:[1,0]
	v_pk_mul_f32 v[28:29], v[28:29], v[48:49] op_sel_hi:[1,0]
	v_pk_mul_f32 v[24:25], v[24:25], v[48:49] op_sel_hi:[1,0]
	global_store_dwordx4 v[36:37], v[28:31], off
	v_pk_mul_f32 v[26:27], v[26:27], v[48:49] op_sel_hi:[1,0]
	v_pk_mul_f32 v[20:21], v[20:21], v[48:49] op_sel_hi:[1,0]
	v_cvt_pk_bf16_f32 v28, v28, v29
	v_cvt_pk_bf16_f32 v29, v30, v31
	global_store_dwordx2 v[42:43], v[28:29], off
	global_store_dwordx4 v[38:39], v[24:27], off
	v_pk_mul_f32 v[22:23], v[22:23], v[48:49] op_sel_hi:[1,0]
	v_pk_mul_f32 v[16:17], v[16:17], v[48:49] op_sel_hi:[1,0]
	v_cvt_pk_bf16_f32 v24, v24, v25
	v_cvt_pk_bf16_f32 v25, v26, v27
	global_store_dwordx2 v[44:45], v[24:25], off
	global_store_dwordx4 v[40:41], v[20:23], off
	v_pk_mul_f32 v[18:19], v[18:19], v[48:49] op_sel_hi:[1,0]
	s_nop 0
	v_cvt_pk_bf16_f32 v20, v20, v21
	v_cvt_pk_bf16_f32 v21, v22, v23
	global_store_dwordx2 v[46:47], v[20:21], off
	global_store_dwordx4 v[34:35], v[16:19], off
	s_nop 1
	v_cvt_pk_bf16_f32 v16, v16, v17
	v_cvt_pk_bf16_f32 v17, v18, v19
	global_store_dwordx2 v[32:33], v[16:17], off
	global_load_dword v28, v[132:133], off offset:704
	v_and_or_b32 v18, v130, s4, v81
	v_lshlrev_b64 v[16:17], 12, v[130:131]
	v_ashrrev_i32_e32 v19, 31, v18
	v_lshlrev_b64 v[18:19], 9, v[18:19]
	v_lshl_add_u64 v[16:17], s[2:3], 0, v[16:17]
	v_lshl_add_u64 v[20:21], v[16:17], 0, v[146:147]
	v_lshl_add_u64 v[18:19], s[0:1], 0, v[18:19]
	v_lshl_add_u64 v[26:27], v[18:19], 0, v[138:139]
	v_lshl_add_u64 v[22:23], v[16:17], 0, v[144:145]
	v_lshl_add_u64 v[24:25], v[16:17], 0, v[142:143]
	v_lshl_add_u64 v[30:31], v[18:19], 0, v[136:137]
	v_lshl_add_u64 v[16:17], v[16:17], 0, v[140:141]
	s_waitcnt vmcnt(0)
	v_fmac_f32_e32 v148, 0x3a800000, v28
	v_mul_f32_e32 v28, 0x4b800000, v148
	v_cmp_gt_f32_e32 vcc, s6, v148
	s_nop 1
	v_cndmask_b32_e32 v28, v148, v28, vcc
	v_rsq_f32_e32 v32, v28
	v_lshl_add_u64 v[28:29], v[18:19], 0, v[134:135]
	v_lshl_add_u64 v[18:19], v[18:19], 0, v[112:113]
	v_mul_f32_e32 v33, 0x45800000, v32
	v_cndmask_b32_e32 v32, v32, v33, vcc
	v_pk_mul_f32 v[14:15], v[14:15], v[32:33] op_sel_hi:[1,0]
	v_pk_mul_f32 v[12:13], v[12:13], v[32:33] op_sel_hi:[1,0]
	v_pk_mul_f32 v[8:9], v[8:9], v[32:33] op_sel_hi:[1,0]
	global_store_dwordx4 v[20:21], v[12:15], off
	v_pk_mul_f32 v[10:11], v[10:11], v[32:33] op_sel_hi:[1,0]
	v_pk_mul_f32 v[4:5], v[4:5], v[32:33] op_sel_hi:[1,0]
	v_cvt_pk_bf16_f32 v12, v12, v13
	v_cvt_pk_bf16_f32 v13, v14, v15
	global_store_dwordx2 v[26:27], v[12:13], off
	global_store_dwordx4 v[22:23], v[8:11], off
	v_pk_mul_f32 v[6:7], v[6:7], v[32:33] op_sel_hi:[1,0]
	v_pk_mul_f32 v[0:1], v[0:1], v[32:33] op_sel_hi:[1,0]
	v_cvt_pk_bf16_f32 v8, v8, v9
	v_cvt_pk_bf16_f32 v9, v10, v11
	global_store_dwordx2 v[28:29], v[8:9], off
	global_store_dwordx4 v[24:25], v[4:7], off
	v_pk_mul_f32 v[2:3], v[2:3], v[32:33] op_sel_hi:[1,0]
	s_nop 0
	v_cvt_pk_bf16_f32 v4, v4, v5
	v_cvt_pk_bf16_f32 v5, v6, v7
	global_store_dwordx2 v[30:31], v[4:5], off
	global_store_dwordx4 v[16:17], v[0:3], off
	s_nop 1
	v_cvt_pk_bf16_f32 v0, v0, v1
	v_cvt_pk_bf16_f32 v1, v2, v3
	global_store_dwordx2 v[18:19], v[0:1], off
	s_waitcnt vmcnt(0)
	s_cbranch_scc0 .LBB0_440
	s_barrier

.LBB0_990:
	ds_read_b128 v[146:149], v155
	ds_read_b128 v[160:163], v155 offset:1024
	ds_read_b128 v[164:167], v155 offset:2048
	ds_read_b128 v[168:171], v155 offset:3072
	ds_read_b128 v[172:175], v156
	ds_read_b128 v[176:179], v156 offset:1024
	ds_read_b128 v[180:183], v156 offset:2048
	ds_read_b128 v[184:187], v156 offset:3072
	s_add_u32 s23, s54, 0xfffc0080
	s_addc_u32 s33, s55, -1
	s_cmp_eq_u32 s75, 12
	s_cselect_b32 s59, s20, s33
	s_cselect_b32 s58, s21, s23
	s_cselect_b32 s57, s19, s74
	s_cselect_b32 s56, s45, s73
	s_add_i32 m0, s51, 0xc000
	ds_read_b128 v[188:191], v157
	ds_read_b128 v[192:195], v157 offset:1024
	ds_read_b128 v[196:199], v157 offset:2048
	ds_read_b128 v[200:203], v157 offset:3072
	ds_read_b128 v[204:207], v157 offset:4096
	ds_read_b128 v[208:211], v157 offset:5120
	ds_read_b128 v[212:215], v157 offset:6144
	ds_read_b128 v[216:219], v157 offset:7168
	global_load_lds_dwordx4 v138, s[54:55]
	s_add_i32 m0, s51, 0xe000
	s_nop 0
	global_load_lds_dwordx4 v140, s[54:55]
	s_waitcnt vmcnt(8)
	s_waitcnt lgkmcnt(0)
	s_barrier
	s_setprio 1
	v_mfma_f32_16x16x32_bf16 v[124:127], v[146:149], v[188:191], v[124:127]
	v_mfma_f32_16x16x32_bf16 v[120:123], v[164:167], v[188:191], v[120:123]
	v_mfma_f32_16x16x32_bf16 v[108:111], v[146:149], v[196:199], v[108:111]
	v_mfma_f32_16x16x32_bf16 v[104:107], v[164:167], v[196:199], v[104:107]
	v_mfma_f32_16x16x32_bf16 v[92:95], v[146:149], v[204:207], v[92:95]
	v_mfma_f32_16x16x32_bf16 v[88:91], v[164:167], v[204:207], v[88:91]
	v_mfma_f32_16x16x32_bf16 v[76:79], v[146:149], v[212:215], v[76:79]
	v_mfma_f32_16x16x32_bf16 v[72:75], v[164:167], v[212:215], v[72:75]
	v_mfma_f32_16x16x32_bf16 v[124:127], v[160:163], v[192:195], v[124:127]
	v_mfma_f32_16x16x32_bf16 v[120:123], v[168:171], v[192:195], v[120:123]
	v_mfma_f32_16x16x32_bf16 v[108:111], v[160:163], v[200:203], v[108:111]
	v_mfma_f32_16x16x32_bf16 v[104:107], v[168:171], v[200:203], v[104:107]
	v_mfma_f32_16x16x32_bf16 v[92:95], v[160:163], v[208:211], v[92:95]
	v_mfma_f32_16x16x32_bf16 v[88:91], v[168:171], v[208:211], v[88:91]
	v_mfma_f32_16x16x32_bf16 v[76:79], v[160:163], v[216:219], v[76:79]
	v_mfma_f32_16x16x32_bf16 v[72:75], v[168:171], v[216:219], v[72:75]
	v_mfma_f32_16x16x32_bf16 v[116:119], v[172:175], v[188:191], v[116:119]
	v_mfma_f32_16x16x32_bf16 v[112:115], v[180:183], v[188:191], v[112:115]
	v_mfma_f32_16x16x32_bf16 v[100:103], v[172:175], v[196:199], v[100:103]
	v_mfma_f32_16x16x32_bf16 v[96:99], v[180:183], v[196:199], v[96:99]
	v_mfma_f32_16x16x32_bf16 v[84:87], v[172:175], v[204:207], v[84:87]
	v_mfma_f32_16x16x32_bf16 v[80:83], v[180:183], v[204:207], v[80:83]
	v_mfma_f32_16x16x32_bf16 v[68:71], v[172:175], v[212:215], v[68:71]
	v_mfma_f32_16x16x32_bf16 v[64:67], v[180:183], v[212:215], v[64:67]
	v_mfma_f32_16x16x32_bf16 v[116:119], v[176:179], v[192:195], v[116:119]
	v_mfma_f32_16x16x32_bf16 v[112:115], v[184:187], v[192:195], v[112:115]
	v_mfma_f32_16x16x32_bf16 v[100:103], v[176:179], v[200:203], v[100:103]
	v_mfma_f32_16x16x32_bf16 v[96:99], v[184:187], v[200:203], v[96:99]
	v_mfma_f32_16x16x32_bf16 v[84:87], v[176:179], v[208:211], v[84:87]
	v_mfma_f32_16x16x32_bf16 v[80:83], v[184:187], v[208:211], v[80:83]
	v_mfma_f32_16x16x32_bf16 v[68:71], v[176:179], v[216:219], v[68:71]
	v_mfma_f32_16x16x32_bf16 v[64:67], v[184:187], v[216:219], v[64:67]
	s_setprio 0
	s_barrier
	s_add_i32 s23, s71, s62
	s_mov_b32 m0, s23
	ds_read_b128 v[188:191], v157 offset:16384
	ds_read_b128 v[192:195], v157 offset:17408
	ds_read_b128 v[196:199], v157 offset:18432
	ds_read_b128 v[200:203], v157 offset:19456
	ds_read_b128 v[204:207], v157 offset:20480
	ds_read_b128 v[208:211], v157 offset:21504
	ds_read_b128 v[212:215], v157 offset:22528
	ds_read_b128 v[216:219], v157 offset:23552
	global_load_lds_dwordx4 v132, s[56:57]
	s_add_i32 m0, s23, 0x2000
	s_add_u32 s76, s56, 0x40000
	s_addc_u32 s77, s57, 0
	s_add_i32 s23, s72, s62
	global_load_lds_dwordx4 v136, s[56:57]
	s_mov_b32 m0, s23
	s_add_u32 s98, s56, s14
	s_addc_u32 s99, s57, s15
	global_load_lds_dwordx4 v132, s[76:77]
	s_add_i32 m0, s23, 0x2000
	s_add_u32 s100, s58, s14
	s_addc_u32 s101, s59, s15
	global_load_lds_dwordx4 v136, s[76:77]
	s_mov_b32 m0, s51
	s_nop 0
	global_load_lds_dwordx4 v130, s[58:59]
	s_mov_b32 m0, s53
	s_nop 0
	global_load_lds_dwordx4 v134, s[58:59]
	s_waitcnt vmcnt(8)
	s_waitcnt lgkmcnt(0)
	s_barrier
	s_setprio 1
	v_mfma_f32_16x16x32_bf16 v[60:63], v[146:149], v[188:191], v[60:63]
	v_mfma_f32_16x16x32_bf16 v[56:59], v[164:167], v[188:191], v[56:59]
	v_mfma_f32_16x16x32_bf16 v[44:47], v[146:149], v[196:199], v[44:47]
	v_mfma_f32_16x16x32_bf16 v[40:43], v[164:167], v[196:199], v[40:43]
	v_mfma_f32_16x16x32_bf16 v[28:31], v[146:149], v[204:207], v[28:31]
	v_mfma_f32_16x16x32_bf16 v[24:27], v[164:167], v[204:207], v[24:27]
	v_mfma_f32_16x16x32_bf16 v[12:15], v[146:149], v[212:215], v[12:15]
	v_mfma_f32_16x16x32_bf16 v[8:11], v[164:167], v[212:215], v[8:11]
	v_mfma_f32_16x16x32_bf16 v[60:63], v[160:163], v[192:195], v[60:63]
	v_mfma_f32_16x16x32_bf16 v[56:59], v[168:171], v[192:195], v[56:59]
	v_mfma_f32_16x16x32_bf16 v[44:47], v[160:163], v[200:203], v[44:47]
	v_mfma_f32_16x16x32_bf16 v[40:43], v[168:171], v[200:203], v[40:43]
	v_mfma_f32_16x16x32_bf16 v[28:31], v[160:163], v[208:211], v[28:31]
	v_mfma_f32_16x16x32_bf16 v[24:27], v[168:171], v[208:211], v[24:27]
	v_mfma_f32_16x16x32_bf16 v[12:15], v[160:163], v[216:219], v[12:15]
	v_mfma_f32_16x16x32_bf16 v[8:11], v[168:171], v[216:219], v[8:11]
	v_mfma_f32_16x16x32_bf16 v[52:55], v[172:175], v[188:191], v[52:55]
	v_mfma_f32_16x16x32_bf16 v[48:51], v[180:183], v[188:191], v[48:51]
	v_mfma_f32_16x16x32_bf16 v[36:39], v[172:175], v[196:199], v[36:39]
	v_mfma_f32_16x16x32_bf16 v[32:35], v[180:183], v[196:199], v[32:35]
	v_mfma_f32_16x16x32_bf16 v[20:23], v[172:175], v[204:207], v[20:23]
	v_mfma_f32_16x16x32_bf16 v[16:19], v[180:183], v[204:207], v[16:19]
	v_mfma_f32_16x16x32_bf16 v[4:7], v[172:175], v[212:215], v[4:7]
	v_mfma_f32_16x16x32_bf16 v[0:3], v[180:183], v[212:215], v[0:3]
	v_mfma_f32_16x16x32_bf16 v[52:55], v[176:179], v[192:195], v[52:55]
	v_mfma_f32_16x16x32_bf16 v[48:51], v[184:187], v[192:195], v[48:51]
	v_mfma_f32_16x16x32_bf16 v[36:39], v[176:179], v[200:203], v[36:39]
	v_mfma_f32_16x16x32_bf16 v[32:35], v[184:187], v[200:203], v[32:35]
	v_mfma_f32_16x16x32_bf16 v[20:23], v[176:179], v[208:211], v[20:23]
	v_mfma_f32_16x16x32_bf16 v[16:19], v[184:187], v[208:211], v[16:19]
	v_mfma_f32_16x16x32_bf16 v[4:7], v[176:179], v[216:219], v[4:7]
	v_mfma_f32_16x16x32_bf16 v[0:3], v[184:187], v[216:219], v[0:3]
	s_setprio 0
	s_barrier
	s_add_i32 s23, 0, 0x18000
	v_add_u32_e32 v159, s23, v153
	s_add_i32 s33, 0, 0x1c000
	ds_read_b128 v[146:149], v159
	ds_read_b128 v[160:163], v159 offset:1024
	ds_read_b128 v[164:167], v159 offset:2048
	ds_read_b128 v[168:171], v159 offset:3072
	v_add_u32_e32 v159, s33, v153
	ds_read_b128 v[172:175], v159
	ds_read_b128 v[176:179], v159 offset:1024
	ds_read_b128 v[180:183], v159 offset:2048
	ds_read_b128 v[184:187], v159 offset:3072
	s_add_u32 s58, s58, 0x40000
	s_addc_u32 s59, s59, 0
	s_mov_b32 m0, s63
	ds_read_b128 v[188:191], v157 offset:32768
	ds_read_b128 v[192:195], v157 offset:33792
	ds_read_b128 v[196:199], v157 offset:34816
	ds_read_b128 v[200:203], v157 offset:35840
	ds_read_b128 v[204:207], v157 offset:36864
	ds_read_b128 v[208:211], v157 offset:37888
	ds_read_b128 v[212:215], v157 offset:38912
	ds_read_b128 v[216:219], v157 offset:39936
	global_load_lds_dwordx4 v130, s[58:59]
	s_mov_b32 m0, s64
	s_nop 0
	global_load_lds_dwordx4 v134, s[58:59]
	s_waitcnt vmcnt(8)
	s_waitcnt lgkmcnt(0)
	s_barrier
	s_setprio 1
	v_mfma_f32_16x16x32_bf16 v[124:127], v[146:149], v[188:191], v[124:127]
	v_mfma_f32_16x16x32_bf16 v[120:123], v[164:167], v[188:191], v[120:123]
	v_mfma_f32_16x16x32_bf16 v[108:111], v[146:149], v[196:199], v[108:111]
	v_mfma_f32_16x16x32_bf16 v[104:107], v[164:167], v[196:199], v[104:107]
	v_mfma_f32_16x16x32_bf16 v[92:95], v[146:149], v[204:207], v[92:95]
	v_mfma_f32_16x16x32_bf16 v[88:91], v[164:167], v[204:207], v[88:91]
	v_mfma_f32_16x16x32_bf16 v[76:79], v[146:149], v[212:215], v[76:79]
	v_mfma_f32_16x16x32_bf16 v[72:75], v[164:167], v[212:215], v[72:75]
	v_mfma_f32_16x16x32_bf16 v[124:127], v[160:163], v[192:195], v[124:127]
	v_mfma_f32_16x16x32_bf16 v[120:123], v[168:171], v[192:195], v[120:123]
	v_mfma_f32_16x16x32_bf16 v[108:111], v[160:163], v[200:203], v[108:111]
	v_mfma_f32_16x16x32_bf16 v[104:107], v[168:171], v[200:203], v[104:107]
	v_mfma_f32_16x16x32_bf16 v[92:95], v[160:163], v[208:211], v[92:95]
	v_mfma_f32_16x16x32_bf16 v[88:91], v[168:171], v[208:211], v[88:91]
	v_mfma_f32_16x16x32_bf16 v[76:79], v[160:163], v[216:219], v[76:79]
	v_mfma_f32_16x16x32_bf16 v[72:75], v[168:171], v[216:219], v[72:75]
	v_mfma_f32_16x16x32_bf16 v[116:119], v[172:175], v[188:191], v[116:119]
	v_mfma_f32_16x16x32_bf16 v[112:115], v[180:183], v[188:191], v[112:115]
	v_mfma_f32_16x16x32_bf16 v[100:103], v[172:175], v[196:199], v[100:103]
	v_mfma_f32_16x16x32_bf16 v[96:99], v[180:183], v[196:199], v[96:99]
	v_mfma_f32_16x16x32_bf16 v[84:87], v[172:175], v[204:207], v[84:87]
	v_mfma_f32_16x16x32_bf16 v[80:83], v[180:183], v[204:207], v[80:83]
	v_mfma_f32_16x16x32_bf16 v[68:71], v[172:175], v[212:215], v[68:71]
	v_mfma_f32_16x16x32_bf16 v[64:67], v[180:183], v[212:215], v[64:67]
	v_mfma_f32_16x16x32_bf16 v[116:119], v[176:179], v[192:195], v[116:119]
	v_mfma_f32_16x16x32_bf16 v[112:115], v[184:187], v[192:195], v[112:115]
	v_mfma_f32_16x16x32_bf16 v[100:103], v[176:179], v[200:203], v[100:103]
	v_mfma_f32_16x16x32_bf16 v[96:99], v[184:187], v[200:203], v[96:99]
	v_mfma_f32_16x16x32_bf16 v[84:87], v[176:179], v[208:211], v[84:87]
	v_mfma_f32_16x16x32_bf16 v[80:83], v[184:187], v[208:211], v[80:83]
	v_mfma_f32_16x16x32_bf16 v[68:71], v[176:179], v[216:219], v[68:71]
	v_mfma_f32_16x16x32_bf16 v[64:67], v[184:187], v[216:219], v[64:67]
	s_setprio 0
	s_barrier
	s_add_i32 s23, s23, s62
	s_mov_b32 m0, s23
	ds_read_b128 v[188:191], v157 offset:49152
	ds_read_b128 v[192:195], v157 offset:50176
	ds_read_b128 v[196:199], v157 offset:51200
	ds_read_b128 v[200:203], v157 offset:52224
	ds_read_b128 v[204:207], v157 offset:53248
	ds_read_b128 v[208:211], v157 offset:54272
	ds_read_b128 v[212:215], v157 offset:55296
	ds_read_b128 v[216:219], v157 offset:56320
	global_load_lds_dwordx4 v132, s[98:99]
	s_add_i32 m0, s23, 0x2000
	s_add_u32 s56, s56, 0x40080
	s_addc_u32 s57, s57, 0
	s_add_i32 s23, s33, s62
	global_load_lds_dwordx4 v136, s[98:99]
	s_mov_b32 m0, s23
	s_nop 0
	global_load_lds_dwordx4 v132, s[56:57]
	s_add_i32 m0, s23, 0x2000
	s_nop 0
	global_load_lds_dwordx4 v136, s[56:57]
	s_mov_b32 m0, s68
	s_nop 0
	global_load_lds_dwordx4 v130, s[100:101]
	s_mov_b32 m0, s69
	s_nop 0
	global_load_lds_dwordx4 v134, s[100:101]
	s_waitcnt vmcnt(8)
	s_waitcnt lgkmcnt(0)
	s_barrier
	s_setprio 1
	v_mfma_f32_16x16x32_bf16 v[60:63], v[146:149], v[188:191], v[60:63]
	v_mfma_f32_16x16x32_bf16 v[56:59], v[164:167], v[188:191], v[56:59]
	v_mfma_f32_16x16x32_bf16 v[44:47], v[146:149], v[196:199], v[44:47]
	v_mfma_f32_16x16x32_bf16 v[40:43], v[164:167], v[196:199], v[40:43]
	v_mfma_f32_16x16x32_bf16 v[28:31], v[146:149], v[204:207], v[28:31]
	v_mfma_f32_16x16x32_bf16 v[24:27], v[164:167], v[204:207], v[24:27]
	v_mfma_f32_16x16x32_bf16 v[12:15], v[146:149], v[212:215], v[12:15]
	v_mfma_f32_16x16x32_bf16 v[8:11], v[164:167], v[212:215], v[8:11]
	v_mfma_f32_16x16x32_bf16 v[60:63], v[160:163], v[192:195], v[60:63]
	v_mfma_f32_16x16x32_bf16 v[56:59], v[168:171], v[192:195], v[56:59]
	v_mfma_f32_16x16x32_bf16 v[44:47], v[160:163], v[200:203], v[44:47]
	v_mfma_f32_16x16x32_bf16 v[40:43], v[168:171], v[200:203], v[40:43]
	v_mfma_f32_16x16x32_bf16 v[28:31], v[160:163], v[208:211], v[28:31]
	v_mfma_f32_16x16x32_bf16 v[24:27], v[168:171], v[208:211], v[24:27]
	v_mfma_f32_16x16x32_bf16 v[12:15], v[160:163], v[216:219], v[12:15]
	v_mfma_f32_16x16x32_bf16 v[8:11], v[168:171], v[216:219], v[8:11]
	v_mfma_f32_16x16x32_bf16 v[52:55], v[172:175], v[188:191], v[52:55]
	v_mfma_f32_16x16x32_bf16 v[48:51], v[180:183], v[188:191], v[48:51]
	v_mfma_f32_16x16x32_bf16 v[36:39], v[172:175], v[196:199], v[36:39]
	v_mfma_f32_16x16x32_bf16 v[32:35], v[180:183], v[196:199], v[32:35]
	v_mfma_f32_16x16x32_bf16 v[20:23], v[172:175], v[204:207], v[20:23]
	v_mfma_f32_16x16x32_bf16 v[16:19], v[180:183], v[204:207], v[16:19]
	v_mfma_f32_16x16x32_bf16 v[4:7], v[172:175], v[212:215], v[4:7]
	v_mfma_f32_16x16x32_bf16 v[0:3], v[180:183], v[212:215], v[0:3]
	v_mfma_f32_16x16x32_bf16 v[52:55], v[176:179], v[192:195], v[52:55]
	v_mfma_f32_16x16x32_bf16 v[48:51], v[184:187], v[192:195], v[48:51]
	v_mfma_f32_16x16x32_bf16 v[36:39], v[176:179], v[200:203], v[36:39]
	v_mfma_f32_16x16x32_bf16 v[32:35], v[184:187], v[200:203], v[32:35]
	v_mfma_f32_16x16x32_bf16 v[20:23], v[176:179], v[208:211], v[20:23]
	v_mfma_f32_16x16x32_bf16 v[16:19], v[184:187], v[208:211], v[16:19]
	v_mfma_f32_16x16x32_bf16 v[4:7], v[176:179], v[216:219], v[4:7]
	v_mfma_f32_16x16x32_bf16 v[0:3], v[184:187], v[216:219], v[0:3]
	s_setprio 0
	s_barrier
	s_add_i32 s75, s75, 2
	s_add_u32 s54, s54, 0x100
	s_addc_u32 s55, s55, 0
	s_add_u32 s73, s73, 0x100
	s_addc_u32 s74, s74, 0
	s_cmp_gt_u32 s75, 13
	s_cbranch_scc0 .LBB0_990
	s_and_b64 vcc, exec, s[16:17]
	s_cbranch_vccz .LBB0_993
	s_barrier

.LBB0_1086:
	ds_read_b128 v[146:149], v155
	ds_read_b128 v[160:163], v155 offset:1024
	ds_read_b128 v[164:167], v155 offset:2048
	ds_read_b128 v[168:171], v155 offset:3072
	ds_read_b128 v[172:175], v156
	ds_read_b128 v[176:179], v156 offset:1024
	ds_read_b128 v[180:183], v156 offset:2048
	ds_read_b128 v[184:187], v156 offset:3072
	s_add_u32 s23, s54, 0xfffc0080
	s_addc_u32 s33, s55, -1
	s_cmp_eq_u32 s82, 12
	s_cselect_b32 s59, s20, s33
	s_cselect_b32 s58, s21, s23
	s_cselect_b32 s57, s47, s81
	s_cselect_b32 s56, s49, s80
	s_add_i32 m0, s64, 0xc000
	ds_read_b128 v[188:191], v157
	ds_read_b128 v[192:195], v157 offset:1024
	ds_read_b128 v[196:199], v157 offset:2048
	ds_read_b128 v[200:203], v157 offset:3072
	ds_read_b128 v[204:207], v157 offset:4096
	ds_read_b128 v[208:211], v157 offset:5120
	ds_read_b128 v[212:215], v157 offset:6144
	ds_read_b128 v[216:219], v157 offset:7168
	global_load_lds_dwordx4 v138, s[54:55]
	s_add_i32 m0, s64, 0xe000
	s_nop 0
	global_load_lds_dwordx4 v140, s[54:55]
	s_waitcnt vmcnt(8)
	s_waitcnt lgkmcnt(0)
	s_barrier
	s_setprio 1
	v_mfma_f32_16x16x32_bf16 v[124:127], v[146:149], v[188:191], v[124:127]
	v_mfma_f32_16x16x32_bf16 v[120:123], v[164:167], v[188:191], v[120:123]
	v_mfma_f32_16x16x32_bf16 v[108:111], v[146:149], v[196:199], v[108:111]
	v_mfma_f32_16x16x32_bf16 v[104:107], v[164:167], v[196:199], v[104:107]
	v_mfma_f32_16x16x32_bf16 v[92:95], v[146:149], v[204:207], v[92:95]
	v_mfma_f32_16x16x32_bf16 v[88:91], v[164:167], v[204:207], v[88:91]
	v_mfma_f32_16x16x32_bf16 v[76:79], v[146:149], v[212:215], v[76:79]
	v_mfma_f32_16x16x32_bf16 v[72:75], v[164:167], v[212:215], v[72:75]
	v_mfma_f32_16x16x32_bf16 v[124:127], v[160:163], v[192:195], v[124:127]
	v_mfma_f32_16x16x32_bf16 v[120:123], v[168:171], v[192:195], v[120:123]
	v_mfma_f32_16x16x32_bf16 v[108:111], v[160:163], v[200:203], v[108:111]
	v_mfma_f32_16x16x32_bf16 v[104:107], v[168:171], v[200:203], v[104:107]
	v_mfma_f32_16x16x32_bf16 v[92:95], v[160:163], v[208:211], v[92:95]
	v_mfma_f32_16x16x32_bf16 v[88:91], v[168:171], v[208:211], v[88:91]
	v_mfma_f32_16x16x32_bf16 v[76:79], v[160:163], v[216:219], v[76:79]
	v_mfma_f32_16x16x32_bf16 v[72:75], v[168:171], v[216:219], v[72:75]
	v_mfma_f32_16x16x32_bf16 v[116:119], v[172:175], v[188:191], v[116:119]
	v_mfma_f32_16x16x32_bf16 v[112:115], v[180:183], v[188:191], v[112:115]
	v_mfma_f32_16x16x32_bf16 v[100:103], v[172:175], v[196:199], v[100:103]
	v_mfma_f32_16x16x32_bf16 v[96:99], v[180:183], v[196:199], v[96:99]
	v_mfma_f32_16x16x32_bf16 v[84:87], v[172:175], v[204:207], v[84:87]
	v_mfma_f32_16x16x32_bf16 v[80:83], v[180:183], v[204:207], v[80:83]
	v_mfma_f32_16x16x32_bf16 v[68:71], v[172:175], v[212:215], v[68:71]
	v_mfma_f32_16x16x32_bf16 v[64:67], v[180:183], v[212:215], v[64:67]
	v_mfma_f32_16x16x32_bf16 v[116:119], v[176:179], v[192:195], v[116:119]
	v_mfma_f32_16x16x32_bf16 v[112:115], v[184:187], v[192:195], v[112:115]
	v_mfma_f32_16x16x32_bf16 v[100:103], v[176:179], v[200:203], v[100:103]
	v_mfma_f32_16x16x32_bf16 v[96:99], v[184:187], v[200:203], v[96:99]
	v_mfma_f32_16x16x32_bf16 v[84:87], v[176:179], v[208:211], v[84:87]
	v_mfma_f32_16x16x32_bf16 v[80:83], v[184:187], v[208:211], v[80:83]
	v_mfma_f32_16x16x32_bf16 v[68:71], v[176:179], v[216:219], v[68:71]
	v_mfma_f32_16x16x32_bf16 v[64:67], v[184:187], v[216:219], v[64:67]
	s_setprio 0
	s_barrier
	s_add_i32 s23, s73, s62
	s_mov_b32 m0, s23
	ds_read_b128 v[188:191], v157 offset:16384
	ds_read_b128 v[192:195], v157 offset:17408
	ds_read_b128 v[196:199], v157 offset:18432
	ds_read_b128 v[200:203], v157 offset:19456
	ds_read_b128 v[204:207], v157 offset:20480
	ds_read_b128 v[208:211], v157 offset:21504
	ds_read_b128 v[212:215], v157 offset:22528
	ds_read_b128 v[216:219], v157 offset:23552
	global_load_lds_dwordx4 v132, s[56:57]
	s_add_i32 m0, s23, 0x2000
	s_add_u32 s84, s56, 0x40000
	s_addc_u32 s85, s57, 0
	s_add_i32 s23, s74, s62
	global_load_lds_dwordx4 v136, s[56:57]
	s_mov_b32 m0, s23
	s_add_u32 s98, s56, s16
	s_addc_u32 s99, s57, s17
	global_load_lds_dwordx4 v132, s[84:85]
	s_add_i32 m0, s23, 0x2000
	s_add_u32 s100, s58, s16
	s_addc_u32 s101, s59, s17
	global_load_lds_dwordx4 v136, s[84:85]
	s_mov_b32 m0, s64
	s_nop 0
	global_load_lds_dwordx4 v130, s[58:59]
	s_mov_b32 m0, s65
	s_nop 0
	global_load_lds_dwordx4 v134, s[58:59]
	s_waitcnt vmcnt(8)
	s_waitcnt lgkmcnt(0)
	s_barrier
	s_setprio 1
	v_mfma_f32_16x16x32_bf16 v[60:63], v[146:149], v[188:191], v[60:63]
	v_mfma_f32_16x16x32_bf16 v[56:59], v[164:167], v[188:191], v[56:59]
	v_mfma_f32_16x16x32_bf16 v[44:47], v[146:149], v[196:199], v[44:47]
	v_mfma_f32_16x16x32_bf16 v[40:43], v[164:167], v[196:199], v[40:43]
	v_mfma_f32_16x16x32_bf16 v[28:31], v[146:149], v[204:207], v[28:31]
	v_mfma_f32_16x16x32_bf16 v[24:27], v[164:167], v[204:207], v[24:27]
	v_mfma_f32_16x16x32_bf16 v[12:15], v[146:149], v[212:215], v[12:15]
	v_mfma_f32_16x16x32_bf16 v[8:11], v[164:167], v[212:215], v[8:11]
	v_mfma_f32_16x16x32_bf16 v[60:63], v[160:163], v[192:195], v[60:63]
	v_mfma_f32_16x16x32_bf16 v[56:59], v[168:171], v[192:195], v[56:59]
	v_mfma_f32_16x16x32_bf16 v[44:47], v[160:163], v[200:203], v[44:47]
	v_mfma_f32_16x16x32_bf16 v[40:43], v[168:171], v[200:203], v[40:43]
	v_mfma_f32_16x16x32_bf16 v[28:31], v[160:163], v[208:211], v[28:31]
	v_mfma_f32_16x16x32_bf16 v[24:27], v[168:171], v[208:211], v[24:27]
	v_mfma_f32_16x16x32_bf16 v[12:15], v[160:163], v[216:219], v[12:15]
	v_mfma_f32_16x16x32_bf16 v[8:11], v[168:171], v[216:219], v[8:11]
	v_mfma_f32_16x16x32_bf16 v[52:55], v[172:175], v[188:191], v[52:55]
	v_mfma_f32_16x16x32_bf16 v[48:51], v[180:183], v[188:191], v[48:51]
	v_mfma_f32_16x16x32_bf16 v[36:39], v[172:175], v[196:199], v[36:39]
	v_mfma_f32_16x16x32_bf16 v[32:35], v[180:183], v[196:199], v[32:35]
	v_mfma_f32_16x16x32_bf16 v[20:23], v[172:175], v[204:207], v[20:23]
	v_mfma_f32_16x16x32_bf16 v[16:19], v[180:183], v[204:207], v[16:19]
	v_mfma_f32_16x16x32_bf16 v[4:7], v[172:175], v[212:215], v[4:7]
	v_mfma_f32_16x16x32_bf16 v[0:3], v[180:183], v[212:215], v[0:3]
	v_mfma_f32_16x16x32_bf16 v[52:55], v[176:179], v[192:195], v[52:55]
	v_mfma_f32_16x16x32_bf16 v[48:51], v[184:187], v[192:195], v[48:51]
	v_mfma_f32_16x16x32_bf16 v[36:39], v[176:179], v[200:203], v[36:39]
	v_mfma_f32_16x16x32_bf16 v[32:35], v[184:187], v[200:203], v[32:35]
	v_mfma_f32_16x16x32_bf16 v[20:23], v[176:179], v[208:211], v[20:23]
	v_mfma_f32_16x16x32_bf16 v[16:19], v[184:187], v[208:211], v[16:19]
	v_mfma_f32_16x16x32_bf16 v[4:7], v[176:179], v[216:219], v[4:7]
	v_mfma_f32_16x16x32_bf16 v[0:3], v[184:187], v[216:219], v[0:3]
	s_setprio 0
	s_barrier
	s_add_i32 s23, 0, 0x18000
	v_add_u32_e32 v159, s23, v153
	s_add_i32 s33, 0, 0x1c000
	ds_read_b128 v[146:149], v159
	ds_read_b128 v[160:163], v159 offset:1024
	ds_read_b128 v[164:167], v159 offset:2048
	ds_read_b128 v[168:171], v159 offset:3072
	v_add_u32_e32 v159, s33, v153
	ds_read_b128 v[172:175], v159
	ds_read_b128 v[176:179], v159 offset:1024
	ds_read_b128 v[180:183], v159 offset:2048
	ds_read_b128 v[184:187], v159 offset:3072
	s_add_u32 s58, s58, 0x40000
	s_addc_u32 s59, s59, 0
	s_mov_b32 m0, s66
	ds_read_b128 v[188:191], v157 offset:32768
	ds_read_b128 v[192:195], v157 offset:33792
	ds_read_b128 v[196:199], v157 offset:34816
	ds_read_b128 v[200:203], v157 offset:35840
	ds_read_b128 v[204:207], v157 offset:36864
	ds_read_b128 v[208:211], v157 offset:37888
	ds_read_b128 v[212:215], v157 offset:38912
	ds_read_b128 v[216:219], v157 offset:39936
	global_load_lds_dwordx4 v130, s[58:59]
	s_mov_b32 m0, s67
	s_nop 0
	global_load_lds_dwordx4 v134, s[58:59]
	s_waitcnt vmcnt(8)
	s_waitcnt lgkmcnt(0)
	s_barrier
	s_setprio 1
	v_mfma_f32_16x16x32_bf16 v[124:127], v[146:149], v[188:191], v[124:127]
	v_mfma_f32_16x16x32_bf16 v[120:123], v[164:167], v[188:191], v[120:123]
	v_mfma_f32_16x16x32_bf16 v[108:111], v[146:149], v[196:199], v[108:111]
	v_mfma_f32_16x16x32_bf16 v[104:107], v[164:167], v[196:199], v[104:107]
	v_mfma_f32_16x16x32_bf16 v[92:95], v[146:149], v[204:207], v[92:95]
	v_mfma_f32_16x16x32_bf16 v[88:91], v[164:167], v[204:207], v[88:91]
	v_mfma_f32_16x16x32_bf16 v[76:79], v[146:149], v[212:215], v[76:79]
	v_mfma_f32_16x16x32_bf16 v[72:75], v[164:167], v[212:215], v[72:75]
	v_mfma_f32_16x16x32_bf16 v[124:127], v[160:163], v[192:195], v[124:127]
	v_mfma_f32_16x16x32_bf16 v[120:123], v[168:171], v[192:195], v[120:123]
	v_mfma_f32_16x16x32_bf16 v[108:111], v[160:163], v[200:203], v[108:111]
	v_mfma_f32_16x16x32_bf16 v[104:107], v[168:171], v[200:203], v[104:107]
	v_mfma_f32_16x16x32_bf16 v[92:95], v[160:163], v[208:211], v[92:95]
	v_mfma_f32_16x16x32_bf16 v[88:91], v[168:171], v[208:211], v[88:91]
	v_mfma_f32_16x16x32_bf16 v[76:79], v[160:163], v[216:219], v[76:79]
	v_mfma_f32_16x16x32_bf16 v[72:75], v[168:171], v[216:219], v[72:75]
	v_mfma_f32_16x16x32_bf16 v[116:119], v[172:175], v[188:191], v[116:119]
	v_mfma_f32_16x16x32_bf16 v[112:115], v[180:183], v[188:191], v[112:115]
	v_mfma_f32_16x16x32_bf16 v[100:103], v[172:175], v[196:199], v[100:103]
	v_mfma_f32_16x16x32_bf16 v[96:99], v[180:183], v[196:199], v[96:99]
	v_mfma_f32_16x16x32_bf16 v[84:87], v[172:175], v[204:207], v[84:87]
	v_mfma_f32_16x16x32_bf16 v[80:83], v[180:183], v[204:207], v[80:83]
	v_mfma_f32_16x16x32_bf16 v[68:71], v[172:175], v[212:215], v[68:71]
	v_mfma_f32_16x16x32_bf16 v[64:67], v[180:183], v[212:215], v[64:67]
	v_mfma_f32_16x16x32_bf16 v[116:119], v[176:179], v[192:195], v[116:119]
	v_mfma_f32_16x16x32_bf16 v[112:115], v[184:187], v[192:195], v[112:115]
	v_mfma_f32_16x16x32_bf16 v[100:103], v[176:179], v[200:203], v[100:103]
	v_mfma_f32_16x16x32_bf16 v[96:99], v[184:187], v[200:203], v[96:99]
	v_mfma_f32_16x16x32_bf16 v[84:87], v[176:179], v[208:211], v[84:87]
	v_mfma_f32_16x16x32_bf16 v[80:83], v[184:187], v[208:211], v[80:83]
	v_mfma_f32_16x16x32_bf16 v[68:71], v[176:179], v[216:219], v[68:71]
	v_mfma_f32_16x16x32_bf16 v[64:67], v[184:187], v[216:219], v[64:67]
	s_setprio 0
	s_barrier
	s_add_i32 s23, s23, s62
	s_mov_b32 m0, s23
	ds_read_b128 v[188:191], v157 offset:49152
	ds_read_b128 v[192:195], v157 offset:50176
	ds_read_b128 v[196:199], v157 offset:51200
	ds_read_b128 v[200:203], v157 offset:52224
	ds_read_b128 v[204:207], v157 offset:53248
	ds_read_b128 v[208:211], v157 offset:54272
	ds_read_b128 v[212:215], v157 offset:55296
	ds_read_b128 v[216:219], v157 offset:56320
	global_load_lds_dwordx4 v132, s[98:99]
	s_add_i32 m0, s23, 0x2000
	s_add_u32 s56, s56, 0x40080
	s_addc_u32 s57, s57, 0
	s_add_i32 s23, s33, s62
	global_load_lds_dwordx4 v136, s[98:99]
	s_mov_b32 m0, s23
	s_nop 0
	global_load_lds_dwordx4 v132, s[56:57]
	s_add_i32 m0, s23, 0x2000
	s_nop 0
	global_load_lds_dwordx4 v136, s[56:57]
	s_mov_b32 m0, s70
	s_nop 0
	global_load_lds_dwordx4 v130, s[100:101]
	s_mov_b32 m0, s71
	s_nop 0
	global_load_lds_dwordx4 v134, s[100:101]
	s_waitcnt vmcnt(8)
	s_waitcnt lgkmcnt(0)
	s_barrier
	s_setprio 1
	v_mfma_f32_16x16x32_bf16 v[60:63], v[146:149], v[188:191], v[60:63]
	v_mfma_f32_16x16x32_bf16 v[56:59], v[164:167], v[188:191], v[56:59]
	v_mfma_f32_16x16x32_bf16 v[44:47], v[146:149], v[196:199], v[44:47]
	v_mfma_f32_16x16x32_bf16 v[40:43], v[164:167], v[196:199], v[40:43]
	v_mfma_f32_16x16x32_bf16 v[28:31], v[146:149], v[204:207], v[28:31]
	v_mfma_f32_16x16x32_bf16 v[24:27], v[164:167], v[204:207], v[24:27]
	v_mfma_f32_16x16x32_bf16 v[12:15], v[146:149], v[212:215], v[12:15]
	v_mfma_f32_16x16x32_bf16 v[8:11], v[164:167], v[212:215], v[8:11]
	v_mfma_f32_16x16x32_bf16 v[60:63], v[160:163], v[192:195], v[60:63]
	v_mfma_f32_16x16x32_bf16 v[56:59], v[168:171], v[192:195], v[56:59]
	v_mfma_f32_16x16x32_bf16 v[44:47], v[160:163], v[200:203], v[44:47]
	v_mfma_f32_16x16x32_bf16 v[40:43], v[168:171], v[200:203], v[40:43]
	v_mfma_f32_16x16x32_bf16 v[28:31], v[160:163], v[208:211], v[28:31]
	v_mfma_f32_16x16x32_bf16 v[24:27], v[168:171], v[208:211], v[24:27]
	v_mfma_f32_16x16x32_bf16 v[12:15], v[160:163], v[216:219], v[12:15]
	v_mfma_f32_16x16x32_bf16 v[8:11], v[168:171], v[216:219], v[8:11]
	v_mfma_f32_16x16x32_bf16 v[52:55], v[172:175], v[188:191], v[52:55]
	v_mfma_f32_16x16x32_bf16 v[48:51], v[180:183], v[188:191], v[48:51]
	v_mfma_f32_16x16x32_bf16 v[36:39], v[172:175], v[196:199], v[36:39]
	v_mfma_f32_16x16x32_bf16 v[32:35], v[180:183], v[196:199], v[32:35]
	v_mfma_f32_16x16x32_bf16 v[20:23], v[172:175], v[204:207], v[20:23]
	v_mfma_f32_16x16x32_bf16 v[16:19], v[180:183], v[204:207], v[16:19]
	v_mfma_f32_16x16x32_bf16 v[4:7], v[172:175], v[212:215], v[4:7]
	v_mfma_f32_16x16x32_bf16 v[0:3], v[180:183], v[212:215], v[0:3]
	v_mfma_f32_16x16x32_bf16 v[52:55], v[176:179], v[192:195], v[52:55]
	v_mfma_f32_16x16x32_bf16 v[48:51], v[184:187], v[192:195], v[48:51]
	v_mfma_f32_16x16x32_bf16 v[36:39], v[176:179], v[200:203], v[36:39]
	v_mfma_f32_16x16x32_bf16 v[32:35], v[184:187], v[200:203], v[32:35]
	v_mfma_f32_16x16x32_bf16 v[20:23], v[176:179], v[208:211], v[20:23]
	v_mfma_f32_16x16x32_bf16 v[16:19], v[184:187], v[208:211], v[16:19]
	v_mfma_f32_16x16x32_bf16 v[4:7], v[176:179], v[216:219], v[4:7]
	v_mfma_f32_16x16x32_bf16 v[0:3], v[184:187], v[216:219], v[0:3]
	s_setprio 0
	s_barrier
	s_add_i32 s82, s82, 2
	s_add_u32 s54, s54, 0x100
	s_addc_u32 s55, s55, 0
	s_add_u32 s80, s80, 0x100
	s_addc_u32 s81, s81, 0
	s_cmp_gt_u32 s82, 13
	s_cbranch_scc0 .LBB0_1086
	s_and_b64 vcc, exec, s[18:19]
	s_cbranch_vccz .LBB0_1089
	s_barrier

.LBB0_1246:
	ds_read_b128 v[146:149], v155
	ds_read_b128 v[160:163], v155 offset:1024
	ds_read_b128 v[164:167], v155 offset:2048
	ds_read_b128 v[168:171], v155 offset:3072
	ds_read_b128 v[172:175], v156
	ds_read_b128 v[176:179], v156 offset:1024
	ds_read_b128 v[180:183], v156 offset:2048
	ds_read_b128 v[184:187], v156 offset:3072
	s_add_u32 s23, s46, 0xfffc0080
	s_addc_u32 s33, s47, -1
	s_cmp_eq_u32 s67, 12
	s_cselect_b32 s51, s20, s33
	s_cselect_b32 s50, s21, s23
	s_cselect_b32 s49, s19, s66
	s_cselect_b32 s48, s37, s65
	s_add_i32 m0, s43, 0xc000
	ds_read_b128 v[188:191], v157
	ds_read_b128 v[192:195], v157 offset:1024
	ds_read_b128 v[196:199], v157 offset:2048
	ds_read_b128 v[200:203], v157 offset:3072
	ds_read_b128 v[204:207], v157 offset:4096
	ds_read_b128 v[208:211], v157 offset:5120
	ds_read_b128 v[212:215], v157 offset:6144
	ds_read_b128 v[216:219], v157 offset:7168
	global_load_lds_dwordx4 v138, s[46:47]
	s_add_i32 m0, s43, 0xe000
	s_nop 0
	global_load_lds_dwordx4 v140, s[46:47]
	s_waitcnt vmcnt(8)
	s_waitcnt lgkmcnt(0)
	s_barrier
	s_setprio 1
	v_mfma_f32_16x16x32_bf16 v[124:127], v[146:149], v[188:191], v[124:127]
	v_mfma_f32_16x16x32_bf16 v[120:123], v[164:167], v[188:191], v[120:123]
	v_mfma_f32_16x16x32_bf16 v[108:111], v[146:149], v[196:199], v[108:111]
	v_mfma_f32_16x16x32_bf16 v[104:107], v[164:167], v[196:199], v[104:107]
	v_mfma_f32_16x16x32_bf16 v[92:95], v[146:149], v[204:207], v[92:95]
	v_mfma_f32_16x16x32_bf16 v[88:91], v[164:167], v[204:207], v[88:91]
	v_mfma_f32_16x16x32_bf16 v[76:79], v[146:149], v[212:215], v[76:79]
	v_mfma_f32_16x16x32_bf16 v[72:75], v[164:167], v[212:215], v[72:75]
	v_mfma_f32_16x16x32_bf16 v[124:127], v[160:163], v[192:195], v[124:127]
	v_mfma_f32_16x16x32_bf16 v[120:123], v[168:171], v[192:195], v[120:123]
	v_mfma_f32_16x16x32_bf16 v[108:111], v[160:163], v[200:203], v[108:111]
	v_mfma_f32_16x16x32_bf16 v[104:107], v[168:171], v[200:203], v[104:107]
	v_mfma_f32_16x16x32_bf16 v[92:95], v[160:163], v[208:211], v[92:95]
	v_mfma_f32_16x16x32_bf16 v[88:91], v[168:171], v[208:211], v[88:91]
	v_mfma_f32_16x16x32_bf16 v[76:79], v[160:163], v[216:219], v[76:79]
	v_mfma_f32_16x16x32_bf16 v[72:75], v[168:171], v[216:219], v[72:75]
	v_mfma_f32_16x16x32_bf16 v[116:119], v[172:175], v[188:191], v[116:119]
	v_mfma_f32_16x16x32_bf16 v[112:115], v[180:183], v[188:191], v[112:115]
	v_mfma_f32_16x16x32_bf16 v[100:103], v[172:175], v[196:199], v[100:103]
	v_mfma_f32_16x16x32_bf16 v[96:99], v[180:183], v[196:199], v[96:99]
	v_mfma_f32_16x16x32_bf16 v[84:87], v[172:175], v[204:207], v[84:87]
	v_mfma_f32_16x16x32_bf16 v[80:83], v[180:183], v[204:207], v[80:83]
	v_mfma_f32_16x16x32_bf16 v[68:71], v[172:175], v[212:215], v[68:71]
	v_mfma_f32_16x16x32_bf16 v[64:67], v[180:183], v[212:215], v[64:67]
	v_mfma_f32_16x16x32_bf16 v[116:119], v[176:179], v[192:195], v[116:119]
	v_mfma_f32_16x16x32_bf16 v[112:115], v[184:187], v[192:195], v[112:115]
	v_mfma_f32_16x16x32_bf16 v[100:103], v[176:179], v[200:203], v[100:103]
	v_mfma_f32_16x16x32_bf16 v[96:99], v[184:187], v[200:203], v[96:99]
	v_mfma_f32_16x16x32_bf16 v[84:87], v[176:179], v[208:211], v[84:87]
	v_mfma_f32_16x16x32_bf16 v[80:83], v[184:187], v[208:211], v[80:83]
	v_mfma_f32_16x16x32_bf16 v[68:71], v[176:179], v[216:219], v[68:71]
	v_mfma_f32_16x16x32_bf16 v[64:67], v[184:187], v[216:219], v[64:67]
	s_setprio 0
	s_barrier
	s_add_i32 s23, s63, s54
	s_mov_b32 m0, s23
	ds_read_b128 v[188:191], v157 offset:16384
	ds_read_b128 v[192:195], v157 offset:17408
	ds_read_b128 v[196:199], v157 offset:18432
	ds_read_b128 v[200:203], v157 offset:19456
	ds_read_b128 v[204:207], v157 offset:20480
	ds_read_b128 v[208:211], v157 offset:21504
	ds_read_b128 v[212:215], v157 offset:22528
	ds_read_b128 v[216:219], v157 offset:23552
	global_load_lds_dwordx4 v132, s[48:49]
	s_add_i32 m0, s23, 0x2000
	s_add_u32 s68, s48, 0x40000
	s_addc_u32 s69, s49, 0
	s_add_i32 s23, s64, s54
	global_load_lds_dwordx4 v136, s[48:49]
	s_mov_b32 m0, s23
	s_add_u32 s98, s48, s14
	s_addc_u32 s99, s49, s15
	global_load_lds_dwordx4 v132, s[68:69]
	s_add_i32 m0, s23, 0x2000
	s_add_u32 s100, s50, s14
	s_addc_u32 s101, s51, s15
	global_load_lds_dwordx4 v136, s[68:69]
	s_mov_b32 m0, s43
	s_nop 0
	global_load_lds_dwordx4 v130, s[50:51]
	s_mov_b32 m0, s45
	s_nop 0
	global_load_lds_dwordx4 v134, s[50:51]
	s_waitcnt vmcnt(8)
	s_waitcnt lgkmcnt(0)
	s_barrier
	s_setprio 1
	v_mfma_f32_16x16x32_bf16 v[60:63], v[146:149], v[188:191], v[60:63]
	v_mfma_f32_16x16x32_bf16 v[56:59], v[164:167], v[188:191], v[56:59]
	v_mfma_f32_16x16x32_bf16 v[44:47], v[146:149], v[196:199], v[44:47]
	v_mfma_f32_16x16x32_bf16 v[40:43], v[164:167], v[196:199], v[40:43]
	v_mfma_f32_16x16x32_bf16 v[28:31], v[146:149], v[204:207], v[28:31]
	v_mfma_f32_16x16x32_bf16 v[24:27], v[164:167], v[204:207], v[24:27]
	v_mfma_f32_16x16x32_bf16 v[12:15], v[146:149], v[212:215], v[12:15]
	v_mfma_f32_16x16x32_bf16 v[8:11], v[164:167], v[212:215], v[8:11]
	v_mfma_f32_16x16x32_bf16 v[60:63], v[160:163], v[192:195], v[60:63]
	v_mfma_f32_16x16x32_bf16 v[56:59], v[168:171], v[192:195], v[56:59]
	v_mfma_f32_16x16x32_bf16 v[44:47], v[160:163], v[200:203], v[44:47]
	v_mfma_f32_16x16x32_bf16 v[40:43], v[168:171], v[200:203], v[40:43]
	v_mfma_f32_16x16x32_bf16 v[28:31], v[160:163], v[208:211], v[28:31]
	v_mfma_f32_16x16x32_bf16 v[24:27], v[168:171], v[208:211], v[24:27]
	v_mfma_f32_16x16x32_bf16 v[12:15], v[160:163], v[216:219], v[12:15]
	v_mfma_f32_16x16x32_bf16 v[8:11], v[168:171], v[216:219], v[8:11]
	v_mfma_f32_16x16x32_bf16 v[52:55], v[172:175], v[188:191], v[52:55]
	v_mfma_f32_16x16x32_bf16 v[48:51], v[180:183], v[188:191], v[48:51]
	v_mfma_f32_16x16x32_bf16 v[36:39], v[172:175], v[196:199], v[36:39]
	v_mfma_f32_16x16x32_bf16 v[32:35], v[180:183], v[196:199], v[32:35]
	v_mfma_f32_16x16x32_bf16 v[20:23], v[172:175], v[204:207], v[20:23]
	v_mfma_f32_16x16x32_bf16 v[16:19], v[180:183], v[204:207], v[16:19]
	v_mfma_f32_16x16x32_bf16 v[4:7], v[172:175], v[212:215], v[4:7]
	v_mfma_f32_16x16x32_bf16 v[0:3], v[180:183], v[212:215], v[0:3]
	v_mfma_f32_16x16x32_bf16 v[52:55], v[176:179], v[192:195], v[52:55]
	v_mfma_f32_16x16x32_bf16 v[48:51], v[184:187], v[192:195], v[48:51]
	v_mfma_f32_16x16x32_bf16 v[36:39], v[176:179], v[200:203], v[36:39]
	v_mfma_f32_16x16x32_bf16 v[32:35], v[184:187], v[200:203], v[32:35]
	v_mfma_f32_16x16x32_bf16 v[20:23], v[176:179], v[208:211], v[20:23]
	v_mfma_f32_16x16x32_bf16 v[16:19], v[184:187], v[208:211], v[16:19]
	v_mfma_f32_16x16x32_bf16 v[4:7], v[176:179], v[216:219], v[4:7]
	v_mfma_f32_16x16x32_bf16 v[0:3], v[184:187], v[216:219], v[0:3]
	s_setprio 0
	s_barrier
	s_add_i32 s23, 0, 0x18000
	v_add_u32_e32 v159, s23, v153
	s_add_i32 s33, 0, 0x1c000
	ds_read_b128 v[146:149], v159
	ds_read_b128 v[160:163], v159 offset:1024
	ds_read_b128 v[164:167], v159 offset:2048
	ds_read_b128 v[168:171], v159 offset:3072
	v_add_u32_e32 v159, s33, v153
	ds_read_b128 v[172:175], v159
	ds_read_b128 v[176:179], v159 offset:1024
	ds_read_b128 v[180:183], v159 offset:2048
	ds_read_b128 v[184:187], v159 offset:3072
	s_add_u32 s50, s50, 0x40000
	s_addc_u32 s51, s51, 0
	s_mov_b32 m0, s55
	ds_read_b128 v[188:191], v157 offset:32768
	ds_read_b128 v[192:195], v157 offset:33792
	ds_read_b128 v[196:199], v157 offset:34816
	ds_read_b128 v[200:203], v157 offset:35840
	ds_read_b128 v[204:207], v157 offset:36864
	ds_read_b128 v[208:211], v157 offset:37888
	ds_read_b128 v[212:215], v157 offset:38912
	ds_read_b128 v[216:219], v157 offset:39936
	global_load_lds_dwordx4 v130, s[50:51]
	s_mov_b32 m0, s56
	s_nop 0
	global_load_lds_dwordx4 v134, s[50:51]
	s_waitcnt vmcnt(8)
	s_waitcnt lgkmcnt(0)
	s_barrier
	s_setprio 1
	v_mfma_f32_16x16x32_bf16 v[124:127], v[146:149], v[188:191], v[124:127]
	v_mfma_f32_16x16x32_bf16 v[120:123], v[164:167], v[188:191], v[120:123]
	v_mfma_f32_16x16x32_bf16 v[108:111], v[146:149], v[196:199], v[108:111]
	v_mfma_f32_16x16x32_bf16 v[104:107], v[164:167], v[196:199], v[104:107]
	v_mfma_f32_16x16x32_bf16 v[92:95], v[146:149], v[204:207], v[92:95]
	v_mfma_f32_16x16x32_bf16 v[88:91], v[164:167], v[204:207], v[88:91]
	v_mfma_f32_16x16x32_bf16 v[76:79], v[146:149], v[212:215], v[76:79]
	v_mfma_f32_16x16x32_bf16 v[72:75], v[164:167], v[212:215], v[72:75]
	v_mfma_f32_16x16x32_bf16 v[124:127], v[160:163], v[192:195], v[124:127]
	v_mfma_f32_16x16x32_bf16 v[120:123], v[168:171], v[192:195], v[120:123]
	v_mfma_f32_16x16x32_bf16 v[108:111], v[160:163], v[200:203], v[108:111]
	v_mfma_f32_16x16x32_bf16 v[104:107], v[168:171], v[200:203], v[104:107]
	v_mfma_f32_16x16x32_bf16 v[92:95], v[160:163], v[208:211], v[92:95]
	v_mfma_f32_16x16x32_bf16 v[88:91], v[168:171], v[208:211], v[88:91]
	v_mfma_f32_16x16x32_bf16 v[76:79], v[160:163], v[216:219], v[76:79]
	v_mfma_f32_16x16x32_bf16 v[72:75], v[168:171], v[216:219], v[72:75]
	v_mfma_f32_16x16x32_bf16 v[116:119], v[172:175], v[188:191], v[116:119]
	v_mfma_f32_16x16x32_bf16 v[112:115], v[180:183], v[188:191], v[112:115]
	v_mfma_f32_16x16x32_bf16 v[100:103], v[172:175], v[196:199], v[100:103]
	v_mfma_f32_16x16x32_bf16 v[96:99], v[180:183], v[196:199], v[96:99]
	v_mfma_f32_16x16x32_bf16 v[84:87], v[172:175], v[204:207], v[84:87]
	v_mfma_f32_16x16x32_bf16 v[80:83], v[180:183], v[204:207], v[80:83]
	v_mfma_f32_16x16x32_bf16 v[68:71], v[172:175], v[212:215], v[68:71]
	v_mfma_f32_16x16x32_bf16 v[64:67], v[180:183], v[212:215], v[64:67]
	v_mfma_f32_16x16x32_bf16 v[116:119], v[176:179], v[192:195], v[116:119]
	v_mfma_f32_16x16x32_bf16 v[112:115], v[184:187], v[192:195], v[112:115]
	v_mfma_f32_16x16x32_bf16 v[100:103], v[176:179], v[200:203], v[100:103]
	v_mfma_f32_16x16x32_bf16 v[96:99], v[184:187], v[200:203], v[96:99]
	v_mfma_f32_16x16x32_bf16 v[84:87], v[176:179], v[208:211], v[84:87]
	v_mfma_f32_16x16x32_bf16 v[80:83], v[184:187], v[208:211], v[80:83]
	v_mfma_f32_16x16x32_bf16 v[68:71], v[176:179], v[216:219], v[68:71]
	v_mfma_f32_16x16x32_bf16 v[64:67], v[184:187], v[216:219], v[64:67]
	s_setprio 0
	s_barrier
	s_add_i32 s23, s23, s54
	s_mov_b32 m0, s23
	ds_read_b128 v[188:191], v157 offset:49152
	ds_read_b128 v[192:195], v157 offset:50176
	ds_read_b128 v[196:199], v157 offset:51200
	ds_read_b128 v[200:203], v157 offset:52224
	ds_read_b128 v[204:207], v157 offset:53248
	ds_read_b128 v[208:211], v157 offset:54272
	ds_read_b128 v[212:215], v157 offset:55296
	ds_read_b128 v[216:219], v157 offset:56320
	global_load_lds_dwordx4 v132, s[98:99]
	s_add_i32 m0, s23, 0x2000
	s_add_u32 s48, s48, 0x40080
	s_addc_u32 s49, s49, 0
	s_add_i32 s23, s33, s54
	global_load_lds_dwordx4 v136, s[98:99]
	s_mov_b32 m0, s23
	s_nop 0
	global_load_lds_dwordx4 v132, s[48:49]
	s_add_i32 m0, s23, 0x2000
	s_nop 0
	global_load_lds_dwordx4 v136, s[48:49]
	s_mov_b32 m0, s60
	s_nop 0
	global_load_lds_dwordx4 v130, s[100:101]
	s_mov_b32 m0, s61
	s_nop 0
	global_load_lds_dwordx4 v134, s[100:101]
	s_waitcnt vmcnt(8)
	s_waitcnt lgkmcnt(0)
	s_barrier
	s_setprio 1
	v_mfma_f32_16x16x32_bf16 v[60:63], v[146:149], v[188:191], v[60:63]
	v_mfma_f32_16x16x32_bf16 v[56:59], v[164:167], v[188:191], v[56:59]
	v_mfma_f32_16x16x32_bf16 v[44:47], v[146:149], v[196:199], v[44:47]
	v_mfma_f32_16x16x32_bf16 v[40:43], v[164:167], v[196:199], v[40:43]
	v_mfma_f32_16x16x32_bf16 v[28:31], v[146:149], v[204:207], v[28:31]
	v_mfma_f32_16x16x32_bf16 v[24:27], v[164:167], v[204:207], v[24:27]
	v_mfma_f32_16x16x32_bf16 v[12:15], v[146:149], v[212:215], v[12:15]
	v_mfma_f32_16x16x32_bf16 v[8:11], v[164:167], v[212:215], v[8:11]
	v_mfma_f32_16x16x32_bf16 v[60:63], v[160:163], v[192:195], v[60:63]
	v_mfma_f32_16x16x32_bf16 v[56:59], v[168:171], v[192:195], v[56:59]
	v_mfma_f32_16x16x32_bf16 v[44:47], v[160:163], v[200:203], v[44:47]
	v_mfma_f32_16x16x32_bf16 v[40:43], v[168:171], v[200:203], v[40:43]
	v_mfma_f32_16x16x32_bf16 v[28:31], v[160:163], v[208:211], v[28:31]
	v_mfma_f32_16x16x32_bf16 v[24:27], v[168:171], v[208:211], v[24:27]
	v_mfma_f32_16x16x32_bf16 v[12:15], v[160:163], v[216:219], v[12:15]
	v_mfma_f32_16x16x32_bf16 v[8:11], v[168:171], v[216:219], v[8:11]
	v_mfma_f32_16x16x32_bf16 v[52:55], v[172:175], v[188:191], v[52:55]
	v_mfma_f32_16x16x32_bf16 v[48:51], v[180:183], v[188:191], v[48:51]
	v_mfma_f32_16x16x32_bf16 v[36:39], v[172:175], v[196:199], v[36:39]
	v_mfma_f32_16x16x32_bf16 v[32:35], v[180:183], v[196:199], v[32:35]
	v_mfma_f32_16x16x32_bf16 v[20:23], v[172:175], v[204:207], v[20:23]
	v_mfma_f32_16x16x32_bf16 v[16:19], v[180:183], v[204:207], v[16:19]
	v_mfma_f32_16x16x32_bf16 v[4:7], v[172:175], v[212:215], v[4:7]
	v_mfma_f32_16x16x32_bf16 v[0:3], v[180:183], v[212:215], v[0:3]
	v_mfma_f32_16x16x32_bf16 v[52:55], v[176:179], v[192:195], v[52:55]
	v_mfma_f32_16x16x32_bf16 v[48:51], v[184:187], v[192:195], v[48:51]
	v_mfma_f32_16x16x32_bf16 v[36:39], v[176:179], v[200:203], v[36:39]
	v_mfma_f32_16x16x32_bf16 v[32:35], v[184:187], v[200:203], v[32:35]
	v_mfma_f32_16x16x32_bf16 v[20:23], v[176:179], v[208:211], v[20:23]
	v_mfma_f32_16x16x32_bf16 v[16:19], v[184:187], v[208:211], v[16:19]
	v_mfma_f32_16x16x32_bf16 v[4:7], v[176:179], v[216:219], v[4:7]
	v_mfma_f32_16x16x32_bf16 v[0:3], v[184:187], v[216:219], v[0:3]
	s_setprio 0
	s_barrier
	s_add_i32 s67, s67, 2
	s_add_u32 s46, s46, 0x100
	s_addc_u32 s47, s47, 0
	s_add_u32 s65, s65, 0x100
	s_addc_u32 s66, s66, 0
	s_cmp_gt_u32 s67, 13
	s_cbranch_scc0 .LBB0_1246
	s_and_b64 vcc, exec, s[16:17]
	s_cbranch_vccz .LBB0_1249
	s_barrier

.LBB0_1342:
	ds_read_b128 v[146:149], v154
	ds_read_b128 v[158:161], v154 offset:1024
	ds_read_b128 v[162:165], v154 offset:2048
	ds_read_b128 v[166:169], v154 offset:3072
	ds_read_b128 v[170:173], v155
	ds_read_b128 v[174:177], v155 offset:1024
	ds_read_b128 v[178:181], v155 offset:2048
	ds_read_b128 v[182:185], v155 offset:3072
	s_add_u32 s23, s40, 0xfffc0080
	s_addc_u32 s33, s41, -1
	s_cmp_eq_u32 s67, 12
	s_cselect_b32 s45, s19, s33
	s_cselect_b32 s44, s20, s23
	s_cselect_b32 s43, s17, s66
	s_cselect_b32 s42, s21, s65
	s_add_i32 m0, s52, 0xc000
	ds_read_b128 v[186:189], v156
	ds_read_b128 v[190:193], v156 offset:1024
	ds_read_b128 v[194:197], v156 offset:2048
	ds_read_b128 v[198:201], v156 offset:3072
	ds_read_b128 v[202:205], v156 offset:4096
	ds_read_b128 v[206:209], v156 offset:5120
	ds_read_b128 v[210:213], v156 offset:6144
	ds_read_b128 v[214:217], v156 offset:7168
	global_load_lds_dwordx4 v138, s[40:41]
	s_add_i32 m0, s52, 0xe000
	s_nop 0
	global_load_lds_dwordx4 v140, s[40:41]
	s_waitcnt vmcnt(8)
	s_waitcnt lgkmcnt(0)
	s_barrier
	s_setprio 1
	v_mfma_f32_16x16x32_bf16 v[116:119], v[146:149], v[186:189], v[116:119]
	v_mfma_f32_16x16x32_bf16 v[112:115], v[162:165], v[186:189], v[112:115]
	v_mfma_f32_16x16x32_bf16 v[100:103], v[146:149], v[194:197], v[100:103]
	v_mfma_f32_16x16x32_bf16 v[96:99], v[162:165], v[194:197], v[96:99]
	v_mfma_f32_16x16x32_bf16 v[84:87], v[146:149], v[202:205], v[84:87]
	v_mfma_f32_16x16x32_bf16 v[80:83], v[162:165], v[202:205], v[80:83]
	v_mfma_f32_16x16x32_bf16 v[72:75], v[146:149], v[210:213], v[72:75]
	v_mfma_f32_16x16x32_bf16 v[64:67], v[162:165], v[210:213], v[64:67]
	v_mfma_f32_16x16x32_bf16 v[116:119], v[158:161], v[190:193], v[116:119]
	v_mfma_f32_16x16x32_bf16 v[112:115], v[166:169], v[190:193], v[112:115]
	v_mfma_f32_16x16x32_bf16 v[100:103], v[158:161], v[198:201], v[100:103]
	v_mfma_f32_16x16x32_bf16 v[96:99], v[166:169], v[198:201], v[96:99]
	v_mfma_f32_16x16x32_bf16 v[84:87], v[158:161], v[206:209], v[84:87]
	v_mfma_f32_16x16x32_bf16 v[80:83], v[166:169], v[206:209], v[80:83]
	v_mfma_f32_16x16x32_bf16 v[72:75], v[158:161], v[214:217], v[72:75]
	v_mfma_f32_16x16x32_bf16 v[64:67], v[166:169], v[214:217], v[64:67]
	v_mfma_f32_16x16x32_bf16 v[124:127], v[170:173], v[186:189], v[124:127]
	v_mfma_f32_16x16x32_bf16 v[120:123], v[178:181], v[186:189], v[120:123]
	v_mfma_f32_16x16x32_bf16 v[108:111], v[170:173], v[194:197], v[108:111]
	v_mfma_f32_16x16x32_bf16 v[104:107], v[178:181], v[194:197], v[104:107]
	v_mfma_f32_16x16x32_bf16 v[92:95], v[170:173], v[202:205], v[92:95]
	v_mfma_f32_16x16x32_bf16 v[88:91], v[178:181], v[202:205], v[88:91]
	v_mfma_f32_16x16x32_bf16 v[76:79], v[170:173], v[210:213], v[76:79]
	v_mfma_f32_16x16x32_bf16 v[68:71], v[178:181], v[210:213], v[68:71]
	v_mfma_f32_16x16x32_bf16 v[124:127], v[174:177], v[190:193], v[124:127]
	v_mfma_f32_16x16x32_bf16 v[120:123], v[182:185], v[190:193], v[120:123]
	v_mfma_f32_16x16x32_bf16 v[108:111], v[174:177], v[198:201], v[108:111]
	v_mfma_f32_16x16x32_bf16 v[104:107], v[182:185], v[198:201], v[104:107]
	v_mfma_f32_16x16x32_bf16 v[92:95], v[174:177], v[206:209], v[92:95]
	v_mfma_f32_16x16x32_bf16 v[88:91], v[182:185], v[206:209], v[88:91]
	v_mfma_f32_16x16x32_bf16 v[76:79], v[174:177], v[214:217], v[76:79]
	v_mfma_f32_16x16x32_bf16 v[68:71], v[182:185], v[214:217], v[68:71]
	s_setprio 0
	s_barrier
	s_add_i32 s23, s61, s50
	s_mov_b32 m0, s23
	ds_read_b128 v[186:189], v156 offset:16384
	ds_read_b128 v[190:193], v156 offset:17408
	ds_read_b128 v[194:197], v156 offset:18432
	ds_read_b128 v[198:201], v156 offset:19456
	ds_read_b128 v[202:205], v156 offset:20480
	ds_read_b128 v[206:209], v156 offset:21504
	ds_read_b128 v[210:213], v156 offset:22528
	ds_read_b128 v[214:217], v156 offset:23552
	global_load_lds_dwordx4 v132, s[42:43]
	s_add_i32 m0, s23, 0x2000
	s_add_u32 s68, s42, 0x40000
	s_addc_u32 s69, s43, 0
	s_add_i32 s23, s62, s50
	global_load_lds_dwordx4 v136, s[42:43]
	s_mov_b32 m0, s23
	s_add_u32 s98, s42, s12
	s_addc_u32 s99, s43, s13
	global_load_lds_dwordx4 v132, s[68:69]
	s_add_i32 m0, s23, 0x2000
	s_add_u32 s100, s44, s12
	s_addc_u32 s101, s45, s13
	global_load_lds_dwordx4 v136, s[68:69]
	s_mov_b32 m0, s52
	s_nop 0
	global_load_lds_dwordx4 v130, s[44:45]
	s_mov_b32 m0, s53
	s_nop 0
	global_load_lds_dwordx4 v134, s[44:45]
	s_waitcnt vmcnt(8)
	s_waitcnt lgkmcnt(0)
	s_barrier
	s_setprio 1
	v_mfma_f32_16x16x32_bf16 v[56:59], v[146:149], v[186:189], v[56:59]
	v_mfma_f32_16x16x32_bf16 v[48:51], v[162:165], v[186:189], v[48:51]
	v_mfma_f32_16x16x32_bf16 v[40:43], v[146:149], v[194:197], v[40:43]
	v_mfma_f32_16x16x32_bf16 v[32:35], v[162:165], v[194:197], v[32:35]
	v_mfma_f32_16x16x32_bf16 v[24:27], v[146:149], v[202:205], v[24:27]
	v_mfma_f32_16x16x32_bf16 v[16:19], v[162:165], v[202:205], v[16:19]
	v_mfma_f32_16x16x32_bf16 v[8:11], v[146:149], v[210:213], v[8:11]
	v_mfma_f32_16x16x32_bf16 v[0:3], v[162:165], v[210:213], v[0:3]
	v_mfma_f32_16x16x32_bf16 v[56:59], v[158:161], v[190:193], v[56:59]
	v_mfma_f32_16x16x32_bf16 v[48:51], v[166:169], v[190:193], v[48:51]
	v_mfma_f32_16x16x32_bf16 v[40:43], v[158:161], v[198:201], v[40:43]
	v_mfma_f32_16x16x32_bf16 v[32:35], v[166:169], v[198:201], v[32:35]
	v_mfma_f32_16x16x32_bf16 v[24:27], v[158:161], v[206:209], v[24:27]
	v_mfma_f32_16x16x32_bf16 v[16:19], v[166:169], v[206:209], v[16:19]
	v_mfma_f32_16x16x32_bf16 v[8:11], v[158:161], v[214:217], v[8:11]
	v_mfma_f32_16x16x32_bf16 v[0:3], v[166:169], v[214:217], v[0:3]
	v_mfma_f32_16x16x32_bf16 v[60:63], v[170:173], v[186:189], v[60:63]
	v_mfma_f32_16x16x32_bf16 v[52:55], v[178:181], v[186:189], v[52:55]
	v_mfma_f32_16x16x32_bf16 v[44:47], v[170:173], v[194:197], v[44:47]
	v_mfma_f32_16x16x32_bf16 v[36:39], v[178:181], v[194:197], v[36:39]
	v_mfma_f32_16x16x32_bf16 v[28:31], v[170:173], v[202:205], v[28:31]
	v_mfma_f32_16x16x32_bf16 v[20:23], v[178:181], v[202:205], v[20:23]
	v_mfma_f32_16x16x32_bf16 v[12:15], v[170:173], v[210:213], v[12:15]
	v_mfma_f32_16x16x32_bf16 v[4:7], v[178:181], v[210:213], v[4:7]
	v_mfma_f32_16x16x32_bf16 v[60:63], v[174:177], v[190:193], v[60:63]
	v_mfma_f32_16x16x32_bf16 v[52:55], v[182:185], v[190:193], v[52:55]
	v_mfma_f32_16x16x32_bf16 v[44:47], v[174:177], v[198:201], v[44:47]
	v_mfma_f32_16x16x32_bf16 v[36:39], v[182:185], v[198:201], v[36:39]
	v_mfma_f32_16x16x32_bf16 v[28:31], v[174:177], v[206:209], v[28:31]
	v_mfma_f32_16x16x32_bf16 v[20:23], v[182:185], v[206:209], v[20:23]
	v_mfma_f32_16x16x32_bf16 v[12:15], v[174:177], v[214:217], v[12:15]
	v_mfma_f32_16x16x32_bf16 v[4:7], v[182:185], v[214:217], v[4:7]
	s_setprio 0
	s_barrier
	s_add_i32 s23, 0, 0x18000
	s_add_i32 s33, 0, 0x1c000
	v_add_u32_e32 v166, s23, v152
	v_add_u32_e32 v182, s33, v152
	ds_read_b128 v[146:149], v166
	ds_read_b128 v[158:161], v166 offset:1024
	ds_read_b128 v[162:165], v166 offset:2048
	ds_read_b128 v[166:169], v166 offset:3072
	ds_read_b128 v[170:173], v182
	ds_read_b128 v[174:177], v182 offset:1024
	ds_read_b128 v[178:181], v182 offset:2048
	ds_read_b128 v[182:185], v182 offset:3072
	s_add_u32 s44, s44, 0x40000
	s_addc_u32 s45, s45, 0
	s_mov_b32 m0, s54
	ds_read_b128 v[186:189], v156 offset:32768
	ds_read_b128 v[190:193], v156 offset:33792
	ds_read_b128 v[194:197], v156 offset:34816
	ds_read_b128 v[198:201], v156 offset:35840
	ds_read_b128 v[202:205], v156 offset:36864
	ds_read_b128 v[206:209], v156 offset:37888
	ds_read_b128 v[210:213], v156 offset:38912
	ds_read_b128 v[214:217], v156 offset:39936
	global_load_lds_dwordx4 v130, s[44:45]
	s_mov_b32 m0, s55
	s_nop 0
	global_load_lds_dwordx4 v134, s[44:45]
	s_waitcnt vmcnt(8)
	s_waitcnt lgkmcnt(0)
	s_barrier
	s_setprio 1
	v_mfma_f32_16x16x32_bf16 v[116:119], v[146:149], v[186:189], v[116:119]
	v_mfma_f32_16x16x32_bf16 v[112:115], v[162:165], v[186:189], v[112:115]
	v_mfma_f32_16x16x32_bf16 v[100:103], v[146:149], v[194:197], v[100:103]
	v_mfma_f32_16x16x32_bf16 v[96:99], v[162:165], v[194:197], v[96:99]
	v_mfma_f32_16x16x32_bf16 v[84:87], v[146:149], v[202:205], v[84:87]
	v_mfma_f32_16x16x32_bf16 v[80:83], v[162:165], v[202:205], v[80:83]
	v_mfma_f32_16x16x32_bf16 v[72:75], v[146:149], v[210:213], v[72:75]
	v_mfma_f32_16x16x32_bf16 v[64:67], v[162:165], v[210:213], v[64:67]
	v_mfma_f32_16x16x32_bf16 v[116:119], v[158:161], v[190:193], v[116:119]
	v_mfma_f32_16x16x32_bf16 v[112:115], v[166:169], v[190:193], v[112:115]
	v_mfma_f32_16x16x32_bf16 v[100:103], v[158:161], v[198:201], v[100:103]
	v_mfma_f32_16x16x32_bf16 v[96:99], v[166:169], v[198:201], v[96:99]
	v_mfma_f32_16x16x32_bf16 v[84:87], v[158:161], v[206:209], v[84:87]
	v_mfma_f32_16x16x32_bf16 v[80:83], v[166:169], v[206:209], v[80:83]
	v_mfma_f32_16x16x32_bf16 v[72:75], v[158:161], v[214:217], v[72:75]
	v_mfma_f32_16x16x32_bf16 v[64:67], v[166:169], v[214:217], v[64:67]
	v_mfma_f32_16x16x32_bf16 v[124:127], v[170:173], v[186:189], v[124:127]
	v_mfma_f32_16x16x32_bf16 v[120:123], v[178:181], v[186:189], v[120:123]
	v_mfma_f32_16x16x32_bf16 v[108:111], v[170:173], v[194:197], v[108:111]
	v_mfma_f32_16x16x32_bf16 v[104:107], v[178:181], v[194:197], v[104:107]
	v_mfma_f32_16x16x32_bf16 v[92:95], v[170:173], v[202:205], v[92:95]
	v_mfma_f32_16x16x32_bf16 v[88:91], v[178:181], v[202:205], v[88:91]
	v_mfma_f32_16x16x32_bf16 v[76:79], v[170:173], v[210:213], v[76:79]
	v_mfma_f32_16x16x32_bf16 v[68:71], v[178:181], v[210:213], v[68:71]
	v_mfma_f32_16x16x32_bf16 v[124:127], v[174:177], v[190:193], v[124:127]
	v_mfma_f32_16x16x32_bf16 v[120:123], v[182:185], v[190:193], v[120:123]
	v_mfma_f32_16x16x32_bf16 v[108:111], v[174:177], v[198:201], v[108:111]
	v_mfma_f32_16x16x32_bf16 v[104:107], v[182:185], v[198:201], v[104:107]
	v_mfma_f32_16x16x32_bf16 v[92:95], v[174:177], v[206:209], v[92:95]
	v_mfma_f32_16x16x32_bf16 v[88:91], v[182:185], v[206:209], v[88:91]
	v_mfma_f32_16x16x32_bf16 v[76:79], v[174:177], v[214:217], v[76:79]
	v_mfma_f32_16x16x32_bf16 v[68:71], v[182:185], v[214:217], v[68:71]
	s_setprio 0
	s_barrier
	s_add_i32 s23, s23, s50
	s_mov_b32 m0, s23
	ds_read_b128 v[186:189], v156 offset:49152
	ds_read_b128 v[190:193], v156 offset:50176
	ds_read_b128 v[194:197], v156 offset:51200
	ds_read_b128 v[198:201], v156 offset:52224
	ds_read_b128 v[202:205], v156 offset:53248
	ds_read_b128 v[206:209], v156 offset:54272
	ds_read_b128 v[210:213], v156 offset:55296
	ds_read_b128 v[214:217], v156 offset:56320
	global_load_lds_dwordx4 v132, s[98:99]
	s_add_i32 m0, s23, 0x2000
	s_add_u32 s42, s42, 0x40080
	s_addc_u32 s43, s43, 0
	s_add_i32 s23, s33, s50
	global_load_lds_dwordx4 v136, s[98:99]
	s_mov_b32 m0, s23
	s_nop 0
	global_load_lds_dwordx4 v132, s[42:43]
	s_add_i32 m0, s23, 0x2000
	s_nop 0
	global_load_lds_dwordx4 v136, s[42:43]
	s_mov_b32 m0, s58
	s_nop 0
	global_load_lds_dwordx4 v130, s[100:101]
	s_mov_b32 m0, s59
	s_nop 0
	global_load_lds_dwordx4 v134, s[100:101]
	s_waitcnt vmcnt(8)
	s_waitcnt lgkmcnt(0)
	s_barrier
	s_setprio 1
	v_mfma_f32_16x16x32_bf16 v[56:59], v[146:149], v[186:189], v[56:59]
	v_mfma_f32_16x16x32_bf16 v[48:51], v[162:165], v[186:189], v[48:51]
	v_mfma_f32_16x16x32_bf16 v[40:43], v[146:149], v[194:197], v[40:43]
	v_mfma_f32_16x16x32_bf16 v[32:35], v[162:165], v[194:197], v[32:35]
	v_mfma_f32_16x16x32_bf16 v[24:27], v[146:149], v[202:205], v[24:27]
	v_mfma_f32_16x16x32_bf16 v[16:19], v[162:165], v[202:205], v[16:19]
	v_mfma_f32_16x16x32_bf16 v[8:11], v[146:149], v[210:213], v[8:11]
	v_mfma_f32_16x16x32_bf16 v[0:3], v[162:165], v[210:213], v[0:3]
	v_mfma_f32_16x16x32_bf16 v[56:59], v[158:161], v[190:193], v[56:59]
	v_mfma_f32_16x16x32_bf16 v[48:51], v[166:169], v[190:193], v[48:51]
	v_mfma_f32_16x16x32_bf16 v[40:43], v[158:161], v[198:201], v[40:43]
	v_mfma_f32_16x16x32_bf16 v[32:35], v[166:169], v[198:201], v[32:35]
	v_mfma_f32_16x16x32_bf16 v[24:27], v[158:161], v[206:209], v[24:27]
	v_mfma_f32_16x16x32_bf16 v[16:19], v[166:169], v[206:209], v[16:19]
	v_mfma_f32_16x16x32_bf16 v[8:11], v[158:161], v[214:217], v[8:11]
	v_mfma_f32_16x16x32_bf16 v[0:3], v[166:169], v[214:217], v[0:3]
	v_mfma_f32_16x16x32_bf16 v[60:63], v[170:173], v[186:189], v[60:63]
	v_mfma_f32_16x16x32_bf16 v[52:55], v[178:181], v[186:189], v[52:55]
	v_mfma_f32_16x16x32_bf16 v[44:47], v[170:173], v[194:197], v[44:47]
	v_mfma_f32_16x16x32_bf16 v[36:39], v[178:181], v[194:197], v[36:39]
	v_mfma_f32_16x16x32_bf16 v[28:31], v[170:173], v[202:205], v[28:31]
	v_mfma_f32_16x16x32_bf16 v[20:23], v[178:181], v[202:205], v[20:23]
	v_mfma_f32_16x16x32_bf16 v[12:15], v[170:173], v[210:213], v[12:15]
	v_mfma_f32_16x16x32_bf16 v[4:7], v[178:181], v[210:213], v[4:7]
	v_mfma_f32_16x16x32_bf16 v[60:63], v[174:177], v[190:193], v[60:63]
	v_mfma_f32_16x16x32_bf16 v[52:55], v[182:185], v[190:193], v[52:55]
	v_mfma_f32_16x16x32_bf16 v[44:47], v[174:177], v[198:201], v[44:47]
	v_mfma_f32_16x16x32_bf16 v[36:39], v[182:185], v[198:201], v[36:39]
	v_mfma_f32_16x16x32_bf16 v[28:31], v[174:177], v[206:209], v[28:31]
	v_mfma_f32_16x16x32_bf16 v[20:23], v[182:185], v[206:209], v[20:23]
	v_mfma_f32_16x16x32_bf16 v[12:15], v[174:177], v[214:217], v[12:15]
	v_mfma_f32_16x16x32_bf16 v[4:7], v[182:185], v[214:217], v[4:7]
	s_setprio 0
	s_barrier
	s_add_i32 s67, s67, 2
	s_add_u32 s40, s40, 0x100
	s_addc_u32 s41, s41, 0
	s_add_u32 s65, s65, 0x100
	s_addc_u32 s66, s66, 0
	s_cmp_gt_u32 s67, 13
	s_cbranch_scc0 .LBB0_1342
	s_and_b64 vcc, exec, s[14:15]
	s_cbranch_vccz .LBB0_1345
	s_barrier

.LBB0_1424:
	ds_read_b128 v[146:149], v156
	ds_read_b128 v[160:163], v156 offset:1024
	ds_read_b128 v[164:167], v156 offset:2048
	ds_read_b128 v[168:171], v156 offset:3072
	ds_read_b128 v[172:175], v157
	ds_read_b128 v[176:179], v157 offset:1024
	ds_read_b128 v[180:183], v157 offset:2048
	ds_read_b128 v[184:187], v157 offset:3072
	s_add_u32 s23, s38, 0xfff50080
	s_addc_u32 s33, s39, -1
	s_cmp_eq_u32 s65, 40
	s_cselect_b32 s43, s1, s33
	s_cselect_b32 s42, s0, s23
	s_cselect_b32 s41, s37, s64
	s_cselect_b32 s40, s36, s63
	s_add_i32 m0, s49, 0xc000
	ds_read_b128 v[188:191], v158
	ds_read_b128 v[192:195], v158 offset:1024
	ds_read_b128 v[196:199], v158 offset:2048
	ds_read_b128 v[200:203], v158 offset:3072
	ds_read_b128 v[204:207], v158 offset:4096
	ds_read_b128 v[208:211], v158 offset:5120
	ds_read_b128 v[212:215], v158 offset:6144
	ds_read_b128 v[216:219], v158 offset:7168
	global_load_lds_dwordx4 v138, s[38:39]
	s_add_i32 m0, s49, 0xe000
	s_nop 0
	global_load_lds_dwordx4 v140, s[38:39]
	s_waitcnt vmcnt(8)
	s_waitcnt lgkmcnt(0)
	s_barrier
	s_setprio 1
	v_mfma_f32_16x16x32_bf16 v[124:127], v[146:149], v[188:191], v[124:127]
	v_mfma_f32_16x16x32_bf16 v[120:123], v[164:167], v[188:191], v[120:123]
	v_mfma_f32_16x16x32_bf16 v[108:111], v[146:149], v[196:199], v[108:111]
	v_mfma_f32_16x16x32_bf16 v[104:107], v[164:167], v[196:199], v[104:107]
	v_mfma_f32_16x16x32_bf16 v[92:95], v[146:149], v[204:207], v[92:95]
	v_mfma_f32_16x16x32_bf16 v[88:91], v[164:167], v[204:207], v[88:91]
	v_mfma_f32_16x16x32_bf16 v[76:79], v[146:149], v[212:215], v[76:79]
	v_mfma_f32_16x16x32_bf16 v[72:75], v[164:167], v[212:215], v[72:75]
	v_mfma_f32_16x16x32_bf16 v[124:127], v[160:163], v[192:195], v[124:127]
	v_mfma_f32_16x16x32_bf16 v[120:123], v[168:171], v[192:195], v[120:123]
	v_mfma_f32_16x16x32_bf16 v[108:111], v[160:163], v[200:203], v[108:111]
	v_mfma_f32_16x16x32_bf16 v[104:107], v[168:171], v[200:203], v[104:107]
	v_mfma_f32_16x16x32_bf16 v[92:95], v[160:163], v[208:211], v[92:95]
	v_mfma_f32_16x16x32_bf16 v[88:91], v[168:171], v[208:211], v[88:91]
	v_mfma_f32_16x16x32_bf16 v[76:79], v[160:163], v[216:219], v[76:79]
	v_mfma_f32_16x16x32_bf16 v[72:75], v[168:171], v[216:219], v[72:75]
	v_mfma_f32_16x16x32_bf16 v[116:119], v[172:175], v[188:191], v[116:119]
	v_mfma_f32_16x16x32_bf16 v[112:115], v[180:183], v[188:191], v[112:115]
	v_mfma_f32_16x16x32_bf16 v[100:103], v[172:175], v[196:199], v[100:103]
	v_mfma_f32_16x16x32_bf16 v[96:99], v[180:183], v[196:199], v[96:99]
	v_mfma_f32_16x16x32_bf16 v[84:87], v[172:175], v[204:207], v[84:87]
	v_mfma_f32_16x16x32_bf16 v[80:83], v[180:183], v[204:207], v[80:83]
	v_mfma_f32_16x16x32_bf16 v[68:71], v[172:175], v[212:215], v[68:71]
	v_mfma_f32_16x16x32_bf16 v[64:67], v[180:183], v[212:215], v[64:67]
	v_mfma_f32_16x16x32_bf16 v[116:119], v[176:179], v[192:195], v[116:119]
	v_mfma_f32_16x16x32_bf16 v[112:115], v[184:187], v[192:195], v[112:115]
	v_mfma_f32_16x16x32_bf16 v[100:103], v[176:179], v[200:203], v[100:103]
	v_mfma_f32_16x16x32_bf16 v[96:99], v[184:187], v[200:203], v[96:99]
	v_mfma_f32_16x16x32_bf16 v[84:87], v[176:179], v[208:211], v[84:87]
	v_mfma_f32_16x16x32_bf16 v[80:83], v[184:187], v[208:211], v[80:83]
	v_mfma_f32_16x16x32_bf16 v[68:71], v[176:179], v[216:219], v[68:71]
	v_mfma_f32_16x16x32_bf16 v[64:67], v[184:187], v[216:219], v[64:67]
	s_setprio 0
	s_barrier
	s_add_i32 s23, s59, s48
	s_mov_b32 m0, s23
	ds_read_b128 v[188:191], v158 offset:16384
	ds_read_b128 v[192:195], v158 offset:17408
	ds_read_b128 v[196:199], v158 offset:18432
	ds_read_b128 v[200:203], v158 offset:19456
	ds_read_b128 v[204:207], v158 offset:20480
	ds_read_b128 v[208:211], v158 offset:21504
	ds_read_b128 v[212:215], v158 offset:22528
	ds_read_b128 v[216:219], v158 offset:23552
	global_load_lds_dwordx4 v132, s[40:41]
	s_add_i32 m0, s23, 0x2000
	s_add_u32 s66, s40, 0xb0000
	s_addc_u32 s67, s41, 0
	s_add_i32 s23, s60, s48
	global_load_lds_dwordx4 v136, s[40:41]
	s_mov_b32 m0, s23
	s_add_u32 s98, s40, s16
	s_addc_u32 s99, s41, s17
	global_load_lds_dwordx4 v132, s[66:67]
	s_add_i32 m0, s23, 0x2000
	s_add_u32 s100, s42, s16
	s_addc_u32 s101, s43, s17
	global_load_lds_dwordx4 v136, s[66:67]
	s_mov_b32 m0, s49
	s_nop 0
	global_load_lds_dwordx4 v130, s[42:43]
	s_mov_b32 m0, s50
	s_nop 0
	global_load_lds_dwordx4 v134, s[42:43]
	s_waitcnt vmcnt(8)
	s_waitcnt lgkmcnt(0)
	s_barrier
	s_setprio 1
	v_mfma_f32_16x16x32_bf16 v[60:63], v[146:149], v[188:191], v[60:63]
	v_mfma_f32_16x16x32_bf16 v[56:59], v[164:167], v[188:191], v[56:59]
	v_mfma_f32_16x16x32_bf16 v[44:47], v[146:149], v[196:199], v[44:47]
	v_mfma_f32_16x16x32_bf16 v[40:43], v[164:167], v[196:199], v[40:43]
	v_mfma_f32_16x16x32_bf16 v[28:31], v[146:149], v[204:207], v[28:31]
	v_mfma_f32_16x16x32_bf16 v[24:27], v[164:167], v[204:207], v[24:27]
	v_mfma_f32_16x16x32_bf16 v[12:15], v[146:149], v[212:215], v[12:15]
	v_mfma_f32_16x16x32_bf16 v[8:11], v[164:167], v[212:215], v[8:11]
	v_mfma_f32_16x16x32_bf16 v[60:63], v[160:163], v[192:195], v[60:63]
	v_mfma_f32_16x16x32_bf16 v[56:59], v[168:171], v[192:195], v[56:59]
	v_mfma_f32_16x16x32_bf16 v[44:47], v[160:163], v[200:203], v[44:47]
	v_mfma_f32_16x16x32_bf16 v[40:43], v[168:171], v[200:203], v[40:43]
	v_mfma_f32_16x16x32_bf16 v[28:31], v[160:163], v[208:211], v[28:31]
	v_mfma_f32_16x16x32_bf16 v[24:27], v[168:171], v[208:211], v[24:27]
	v_mfma_f32_16x16x32_bf16 v[12:15], v[160:163], v[216:219], v[12:15]
	v_mfma_f32_16x16x32_bf16 v[8:11], v[168:171], v[216:219], v[8:11]
	v_mfma_f32_16x16x32_bf16 v[52:55], v[172:175], v[188:191], v[52:55]
	v_mfma_f32_16x16x32_bf16 v[48:51], v[180:183], v[188:191], v[48:51]
	v_mfma_f32_16x16x32_bf16 v[36:39], v[172:175], v[196:199], v[36:39]
	v_mfma_f32_16x16x32_bf16 v[32:35], v[180:183], v[196:199], v[32:35]
	v_mfma_f32_16x16x32_bf16 v[20:23], v[172:175], v[204:207], v[20:23]
	v_mfma_f32_16x16x32_bf16 v[16:19], v[180:183], v[204:207], v[16:19]
	v_mfma_f32_16x16x32_bf16 v[4:7], v[172:175], v[212:215], v[4:7]
	v_mfma_f32_16x16x32_bf16 v[0:3], v[180:183], v[212:215], v[0:3]
	v_mfma_f32_16x16x32_bf16 v[52:55], v[176:179], v[192:195], v[52:55]
	v_mfma_f32_16x16x32_bf16 v[48:51], v[184:187], v[192:195], v[48:51]
	v_mfma_f32_16x16x32_bf16 v[36:39], v[176:179], v[200:203], v[36:39]
	v_mfma_f32_16x16x32_bf16 v[32:35], v[184:187], v[200:203], v[32:35]
	v_mfma_f32_16x16x32_bf16 v[20:23], v[176:179], v[208:211], v[20:23]
	v_mfma_f32_16x16x32_bf16 v[16:19], v[184:187], v[208:211], v[16:19]
	v_mfma_f32_16x16x32_bf16 v[4:7], v[176:179], v[216:219], v[4:7]
	v_mfma_f32_16x16x32_bf16 v[0:3], v[184:187], v[216:219], v[0:3]
	s_setprio 0
	s_barrier
	s_add_i32 s23, 0, 0x18000
	s_add_i32 s33, 0, 0x1c000
	v_add_u32_e32 v168, s23, v154
	v_add_u32_e32 v184, s33, v154
	ds_read_b128 v[146:149], v168
	ds_read_b128 v[160:163], v168 offset:1024
	ds_read_b128 v[164:167], v168 offset:2048
	ds_read_b128 v[168:171], v168 offset:3072
	ds_read_b128 v[172:175], v184
	ds_read_b128 v[176:179], v184 offset:1024
	ds_read_b128 v[180:183], v184 offset:2048
	ds_read_b128 v[184:187], v184 offset:3072
	s_add_u32 s42, s42, 0xb0000
	s_addc_u32 s43, s43, 0
	s_mov_b32 m0, s51
	ds_read_b128 v[188:191], v158 offset:32768
	ds_read_b128 v[192:195], v158 offset:33792
	ds_read_b128 v[196:199], v158 offset:34816
	ds_read_b128 v[200:203], v158 offset:35840
	ds_read_b128 v[204:207], v158 offset:36864
	ds_read_b128 v[208:211], v158 offset:37888
	ds_read_b128 v[212:215], v158 offset:38912
	ds_read_b128 v[216:219], v158 offset:39936
	global_load_lds_dwordx4 v130, s[42:43]
	s_mov_b32 m0, s52
	s_nop 0
	global_load_lds_dwordx4 v134, s[42:43]
	s_waitcnt vmcnt(8)
	s_waitcnt lgkmcnt(0)
	s_barrier
	s_setprio 1
	v_mfma_f32_16x16x32_bf16 v[124:127], v[146:149], v[188:191], v[124:127]
	v_mfma_f32_16x16x32_bf16 v[120:123], v[164:167], v[188:191], v[120:123]
	v_mfma_f32_16x16x32_bf16 v[108:111], v[146:149], v[196:199], v[108:111]
	v_mfma_f32_16x16x32_bf16 v[104:107], v[164:167], v[196:199], v[104:107]
	v_mfma_f32_16x16x32_bf16 v[92:95], v[146:149], v[204:207], v[92:95]
	v_mfma_f32_16x16x32_bf16 v[88:91], v[164:167], v[204:207], v[88:91]
	v_mfma_f32_16x16x32_bf16 v[76:79], v[146:149], v[212:215], v[76:79]
	v_mfma_f32_16x16x32_bf16 v[72:75], v[164:167], v[212:215], v[72:75]
	v_mfma_f32_16x16x32_bf16 v[124:127], v[160:163], v[192:195], v[124:127]
	v_mfma_f32_16x16x32_bf16 v[120:123], v[168:171], v[192:195], v[120:123]
	v_mfma_f32_16x16x32_bf16 v[108:111], v[160:163], v[200:203], v[108:111]
	v_mfma_f32_16x16x32_bf16 v[104:107], v[168:171], v[200:203], v[104:107]
	v_mfma_f32_16x16x32_bf16 v[92:95], v[160:163], v[208:211], v[92:95]
	v_mfma_f32_16x16x32_bf16 v[88:91], v[168:171], v[208:211], v[88:91]
	v_mfma_f32_16x16x32_bf16 v[76:79], v[160:163], v[216:219], v[76:79]
	v_mfma_f32_16x16x32_bf16 v[72:75], v[168:171], v[216:219], v[72:75]
	v_mfma_f32_16x16x32_bf16 v[116:119], v[172:175], v[188:191], v[116:119]
	v_mfma_f32_16x16x32_bf16 v[112:115], v[180:183], v[188:191], v[112:115]
	v_mfma_f32_16x16x32_bf16 v[100:103], v[172:175], v[196:199], v[100:103]
	v_mfma_f32_16x16x32_bf16 v[96:99], v[180:183], v[196:199], v[96:99]
	v_mfma_f32_16x16x32_bf16 v[84:87], v[172:175], v[204:207], v[84:87]
	v_mfma_f32_16x16x32_bf16 v[80:83], v[180:183], v[204:207], v[80:83]
	v_mfma_f32_16x16x32_bf16 v[68:71], v[172:175], v[212:215], v[68:71]
	v_mfma_f32_16x16x32_bf16 v[64:67], v[180:183], v[212:215], v[64:67]
	v_mfma_f32_16x16x32_bf16 v[116:119], v[176:179], v[192:195], v[116:119]
	v_mfma_f32_16x16x32_bf16 v[112:115], v[184:187], v[192:195], v[112:115]
	v_mfma_f32_16x16x32_bf16 v[100:103], v[176:179], v[200:203], v[100:103]
	v_mfma_f32_16x16x32_bf16 v[96:99], v[184:187], v[200:203], v[96:99]
	v_mfma_f32_16x16x32_bf16 v[84:87], v[176:179], v[208:211], v[84:87]
	v_mfma_f32_16x16x32_bf16 v[80:83], v[184:187], v[208:211], v[80:83]
	v_mfma_f32_16x16x32_bf16 v[68:71], v[176:179], v[216:219], v[68:71]
	v_mfma_f32_16x16x32_bf16 v[64:67], v[184:187], v[216:219], v[64:67]
	s_setprio 0
	s_barrier
	s_add_i32 s23, s23, s48
	s_mov_b32 m0, s23
	ds_read_b128 v[188:191], v158 offset:49152
	ds_read_b128 v[192:195], v158 offset:50176
	ds_read_b128 v[196:199], v158 offset:51200
	ds_read_b128 v[200:203], v158 offset:52224
	ds_read_b128 v[204:207], v158 offset:53248
	ds_read_b128 v[208:211], v158 offset:54272
	ds_read_b128 v[212:215], v158 offset:55296
	ds_read_b128 v[216:219], v158 offset:56320
	global_load_lds_dwordx4 v132, s[98:99]
	s_add_i32 m0, s23, 0x2000
	s_add_u32 s40, s40, 0xb0080
	s_addc_u32 s41, s41, 0
	s_add_i32 s23, s33, s48
	global_load_lds_dwordx4 v136, s[98:99]
	s_mov_b32 m0, s23
	s_nop 0
	global_load_lds_dwordx4 v132, s[40:41]
	s_add_i32 m0, s23, 0x2000
	s_nop 0
	global_load_lds_dwordx4 v136, s[40:41]
	s_mov_b32 m0, s56
	s_nop 0
	global_load_lds_dwordx4 v130, s[100:101]
	s_mov_b32 m0, s57
	s_nop 0
	global_load_lds_dwordx4 v134, s[100:101]
	s_waitcnt vmcnt(8)
	s_waitcnt lgkmcnt(0)
	s_barrier
	s_setprio 1
	v_mfma_f32_16x16x32_bf16 v[60:63], v[146:149], v[188:191], v[60:63]
	v_mfma_f32_16x16x32_bf16 v[56:59], v[164:167], v[188:191], v[56:59]
	v_mfma_f32_16x16x32_bf16 v[44:47], v[146:149], v[196:199], v[44:47]
	v_mfma_f32_16x16x32_bf16 v[40:43], v[164:167], v[196:199], v[40:43]
	v_mfma_f32_16x16x32_bf16 v[28:31], v[146:149], v[204:207], v[28:31]
	v_mfma_f32_16x16x32_bf16 v[24:27], v[164:167], v[204:207], v[24:27]
	v_mfma_f32_16x16x32_bf16 v[12:15], v[146:149], v[212:215], v[12:15]
	v_mfma_f32_16x16x32_bf16 v[8:11], v[164:167], v[212:215], v[8:11]
	v_mfma_f32_16x16x32_bf16 v[60:63], v[160:163], v[192:195], v[60:63]
	v_mfma_f32_16x16x32_bf16 v[56:59], v[168:171], v[192:195], v[56:59]
	v_mfma_f32_16x16x32_bf16 v[44:47], v[160:163], v[200:203], v[44:47]
	v_mfma_f32_16x16x32_bf16 v[40:43], v[168:171], v[200:203], v[40:43]
	v_mfma_f32_16x16x32_bf16 v[28:31], v[160:163], v[208:211], v[28:31]
	v_mfma_f32_16x16x32_bf16 v[24:27], v[168:171], v[208:211], v[24:27]
	v_mfma_f32_16x16x32_bf16 v[12:15], v[160:163], v[216:219], v[12:15]
	v_mfma_f32_16x16x32_bf16 v[8:11], v[168:171], v[216:219], v[8:11]
	v_mfma_f32_16x16x32_bf16 v[52:55], v[172:175], v[188:191], v[52:55]
	v_mfma_f32_16x16x32_bf16 v[48:51], v[180:183], v[188:191], v[48:51]
	v_mfma_f32_16x16x32_bf16 v[36:39], v[172:175], v[196:199], v[36:39]
	v_mfma_f32_16x16x32_bf16 v[32:35], v[180:183], v[196:199], v[32:35]
	v_mfma_f32_16x16x32_bf16 v[20:23], v[172:175], v[204:207], v[20:23]
	v_mfma_f32_16x16x32_bf16 v[16:19], v[180:183], v[204:207], v[16:19]
	v_mfma_f32_16x16x32_bf16 v[4:7], v[172:175], v[212:215], v[4:7]
	v_mfma_f32_16x16x32_bf16 v[0:3], v[180:183], v[212:215], v[0:3]
	v_mfma_f32_16x16x32_bf16 v[52:55], v[176:179], v[192:195], v[52:55]
	v_mfma_f32_16x16x32_bf16 v[48:51], v[184:187], v[192:195], v[48:51]
	v_mfma_f32_16x16x32_bf16 v[36:39], v[176:179], v[200:203], v[36:39]
	v_mfma_f32_16x16x32_bf16 v[32:35], v[184:187], v[200:203], v[32:35]
	v_mfma_f32_16x16x32_bf16 v[20:23], v[176:179], v[208:211], v[20:23]
	v_mfma_f32_16x16x32_bf16 v[16:19], v[184:187], v[208:211], v[16:19]
	v_mfma_f32_16x16x32_bf16 v[4:7], v[176:179], v[216:219], v[4:7]
	v_mfma_f32_16x16x32_bf16 v[0:3], v[184:187], v[216:219], v[0:3]
	s_setprio 0
	s_barrier
	s_add_i32 s65, s65, 2
	s_add_u32 s38, s38, 0x100
	s_addc_u32 s39, s39, 0
	s_add_u32 s63, s63, 0x100
	s_addc_u32 s64, s64, 0
	s_cmp_gt_u32 s65, 41
	s_cbranch_scc0 .LBB0_1424
	s_and_b64 vcc, exec, s[18:19]
	s_cbranch_vccz .LBB0_1427
	s_barrier
